# GEMM K-loops: LDS fragment waits moved in front of the phase barrier and removed from the MFMA section (barrier / 16 MFMA / barrier), on top of removing the per-phase s_setprio flips
# baseline (speedup 1.0000x reference)
.LBB0_197:
	ds_read_b128 v[144:147], v151
	ds_read_b128 v[154:157], v151 offset:1024
	ds_read_b128 v[158:161], v151 offset:2048
	ds_read_b128 v[162:165], v151 offset:3072
	s_add_u32 s18, s16, 0xfff80080
	s_addc_u32 s19, s17, -1
	s_cmp_eq_u32 s78, 28
	s_cselect_b32 s21, s5, s19
	s_cselect_b32 s20, s9, s18
	s_cselect_b32 s19, s7, s77
	s_cselect_b32 s18, s15, s76
	v_lshl_add_u64 v[198:199], s[16:17], 0, v[136:137]
	s_add_i32 m0, s24, 0xc000
	ds_read_b128 v[166:169], v152
	ds_read_b128 v[170:173], v152 offset:1024
	ds_read_b128 v[174:177], v152 offset:2048
	ds_read_b128 v[178:181], v152 offset:3072
	ds_read_b128 v[182:185], v152 offset:4096
	ds_read_b128 v[186:189], v152 offset:5120
	ds_read_b128 v[190:193], v152 offset:6144
	ds_read_b128 v[194:197], v152 offset:7168
	global_load_lds_dwordx4 v[198:199], off
	v_lshl_add_u64 v[198:199], s[16:17], 0, v[138:139]
	s_add_i32 m0, s24, 0xe000
	s_nop 0
	global_load_lds_dwordx4 v[198:199], off
	s_waitcnt lgkmcnt(0)
	s_barrier
	v_mfma_f32_16x16x32_f16 v[124:127], v[144:147], v[166:169], v[124:127]
	v_mfma_f32_16x16x32_f16 v[120:123], v[158:161], v[166:169], v[120:123]
	v_mfma_f32_16x16x32_f16 v[108:111], v[144:147], v[174:177], v[108:111]
	v_mfma_f32_16x16x32_f16 v[104:107], v[158:161], v[174:177], v[104:107]
	v_mfma_f32_16x16x32_f16 v[92:95], v[144:147], v[182:185], v[92:95]
	v_mfma_f32_16x16x32_f16 v[88:91], v[158:161], v[182:185], v[88:91]
	v_mfma_f32_16x16x32_f16 v[76:79], v[144:147], v[190:193], v[76:79]
	v_mfma_f32_16x16x32_f16 v[72:75], v[158:161], v[190:193], v[72:75]
	v_mfma_f32_16x16x32_f16 v[124:127], v[154:157], v[170:173], v[124:127]
	v_mfma_f32_16x16x32_f16 v[120:123], v[162:165], v[170:173], v[120:123]
	v_mfma_f32_16x16x32_f16 v[108:111], v[154:157], v[178:181], v[108:111]
	v_mfma_f32_16x16x32_f16 v[104:107], v[162:165], v[178:181], v[104:107]
	v_mfma_f32_16x16x32_f16 v[92:95], v[154:157], v[186:189], v[92:95]
	v_mfma_f32_16x16x32_f16 v[88:91], v[162:165], v[186:189], v[88:91]
	v_mfma_f32_16x16x32_f16 v[76:79], v[154:157], v[194:197], v[76:79]
	v_mfma_f32_16x16x32_f16 v[72:75], v[162:165], v[194:197], v[72:75]
	s_barrier
	s_add_i32 s79, s68, s23
	v_lshl_add_u64 v[214:215], s[18:19], 0, v[130:131]
	s_mov_b32 m0, s79
	ds_read_b128 v[198:201], v153
	ds_read_b128 v[202:205], v153 offset:1024
	ds_read_b128 v[206:209], v153 offset:2048
	ds_read_b128 v[210:213], v153 offset:3072
	global_load_lds_dwordx4 v[214:215], off
	v_lshl_add_u64 v[216:217], s[18:19], 0, v[134:135]
	s_add_i32 m0, s79, 0x2000
	s_nop 0
	global_load_lds_dwordx4 v[216:217], off
	s_waitcnt lgkmcnt(0)
	s_barrier
	v_mfma_f32_16x16x32_f16 v[116:119], v[198:201], v[166:169], v[116:119]
	v_mfma_f32_16x16x32_f16 v[112:115], v[206:209], v[166:169], v[112:115]
	v_mfma_f32_16x16x32_f16 v[100:103], v[198:201], v[174:177], v[100:103]
	v_mfma_f32_16x16x32_f16 v[96:99], v[206:209], v[174:177], v[96:99]
	v_mfma_f32_16x16x32_f16 v[84:87], v[198:201], v[182:185], v[84:87]
	v_mfma_f32_16x16x32_f16 v[80:83], v[206:209], v[182:185], v[80:83]
	v_mfma_f32_16x16x32_f16 v[68:71], v[198:201], v[190:193], v[68:71]
	v_mfma_f32_16x16x32_f16 v[64:67], v[206:209], v[190:193], v[64:67]
	v_mfma_f32_16x16x32_f16 v[116:119], v[202:205], v[170:173], v[116:119]
	v_mfma_f32_16x16x32_f16 v[112:115], v[210:213], v[170:173], v[112:115]
	v_mfma_f32_16x16x32_f16 v[100:103], v[202:205], v[178:181], v[100:103]
	v_mfma_f32_16x16x32_f16 v[96:99], v[210:213], v[178:181], v[96:99]
	v_mfma_f32_16x16x32_f16 v[84:87], v[202:205], v[186:189], v[84:87]
	v_mfma_f32_16x16x32_f16 v[80:83], v[210:213], v[186:189], v[80:83]
	v_mfma_f32_16x16x32_f16 v[68:71], v[202:205], v[194:197], v[68:71]
	v_mfma_f32_16x16x32_f16 v[64:67], v[210:213], v[194:197], v[64:67]
	s_mov_b32 m0, s24
	v_lshl_add_u64 v[218:219], s[20:21], 0, v[128:129]
	s_barrier
	ds_read_b128 v[166:169], v152 offset:16384
	ds_read_b128 v[170:173], v152 offset:17408
	ds_read_b128 v[174:177], v152 offset:18432
	ds_read_b128 v[178:181], v152 offset:19456
	ds_read_b128 v[182:185], v152 offset:20480
	ds_read_b128 v[186:189], v152 offset:21504
	ds_read_b128 v[190:193], v152 offset:22528
	ds_read_b128 v[194:197], v152 offset:23552
	global_load_lds_dwordx4 v[218:219], off
	v_lshl_add_u64 v[220:221], s[20:21], 0, v[132:133]
	s_mov_b32 m0, s25
	s_nop 0
	global_load_lds_dwordx4 v[220:221], off
	s_waitcnt lgkmcnt(0)
	s_barrier
	v_mfma_f32_16x16x32_f16 v[60:63], v[144:147], v[166:169], v[60:63]
	v_mfma_f32_16x16x32_f16 v[56:59], v[158:161], v[166:169], v[56:59]
	v_mfma_f32_16x16x32_f16 v[44:47], v[144:147], v[174:177], v[44:47]
	v_mfma_f32_16x16x32_f16 v[40:43], v[158:161], v[174:177], v[40:43]
	v_mfma_f32_16x16x32_f16 v[28:31], v[144:147], v[182:185], v[28:31]
	v_mfma_f32_16x16x32_f16 v[24:27], v[158:161], v[182:185], v[24:27]
	v_mfma_f32_16x16x32_f16 v[12:15], v[144:147], v[190:193], v[12:15]
	v_mfma_f32_16x16x32_f16 v[8:11], v[158:161], v[190:193], v[8:11]
	v_mfma_f32_16x16x32_f16 v[60:63], v[154:157], v[170:173], v[60:63]
	v_mfma_f32_16x16x32_f16 v[56:59], v[162:165], v[170:173], v[56:59]
	v_mfma_f32_16x16x32_f16 v[44:47], v[154:157], v[178:181], v[44:47]
	v_mfma_f32_16x16x32_f16 v[40:43], v[162:165], v[178:181], v[40:43]
	v_mfma_f32_16x16x32_f16 v[28:31], v[154:157], v[186:189], v[28:31]
	v_mfma_f32_16x16x32_f16 v[24:27], v[162:165], v[186:189], v[24:27]
	v_mfma_f32_16x16x32_f16 v[12:15], v[154:157], v[194:197], v[12:15]
	v_mfma_f32_16x16x32_f16 v[8:11], v[162:165], v[194:197], v[8:11]
	s_barrier
	s_add_u32 s80, s18, 0x80000
	s_addc_u32 s81, s19, 0
	s_add_i32 s79, s69, s23
	v_lshl_add_u64 v[144:145], s[80:81], 0, v[130:131]
	s_mov_b32 m0, s79
	s_nop 0
	global_load_lds_dwordx4 v[144:145], off
	v_lshl_add_u64 v[144:145], s[80:81], 0, v[134:135]
	s_add_i32 m0, s79, 0x2000
	s_nop 0
	global_load_lds_dwordx4 v[144:145], off
	s_waitcnt vmcnt(6)
	s_barrier
	v_mfma_f32_16x16x32_f16 v[52:55], v[198:201], v[166:169], v[52:55]
	v_mfma_f32_16x16x32_f16 v[48:51], v[206:209], v[166:169], v[48:51]
	v_mfma_f32_16x16x32_f16 v[36:39], v[198:201], v[174:177], v[36:39]
	v_mfma_f32_16x16x32_f16 v[32:35], v[206:209], v[174:177], v[32:35]
	v_mfma_f32_16x16x32_f16 v[20:23], v[198:201], v[182:185], v[20:23]
	v_mfma_f32_16x16x32_f16 v[16:19], v[206:209], v[182:185], v[16:19]
	v_mfma_f32_16x16x32_f16 v[4:7], v[198:201], v[190:193], v[4:7]
	v_mfma_f32_16x16x32_f16 v[0:3], v[206:209], v[190:193], v[0:3]
	v_mfma_f32_16x16x32_f16 v[52:55], v[202:205], v[170:173], v[52:55]
	v_mfma_f32_16x16x32_f16 v[48:51], v[210:213], v[170:173], v[48:51]
	v_mfma_f32_16x16x32_f16 v[36:39], v[202:205], v[178:181], v[36:39]
	v_mfma_f32_16x16x32_f16 v[32:35], v[210:213], v[178:181], v[32:35]
	v_mfma_f32_16x16x32_f16 v[20:23], v[202:205], v[186:189], v[20:23]
	v_mfma_f32_16x16x32_f16 v[16:19], v[210:213], v[186:189], v[16:19]
	v_mfma_f32_16x16x32_f16 v[4:7], v[202:205], v[194:197], v[4:7]
	v_mfma_f32_16x16x32_f16 v[0:3], v[210:213], v[194:197], v[0:3]
	s_add_i32 s79, 0, 0x18000
	v_add_u32_e32 v162, s79, v149
	s_barrier
	ds_read_b128 v[144:147], v162
	ds_read_b128 v[154:157], v162 offset:1024
	ds_read_b128 v[158:161], v162 offset:2048
	ds_read_b128 v[162:165], v162 offset:3072
	s_add_u32 s20, s20, 0x80000
	s_addc_u32 s21, s21, 0
	s_mov_b32 m0, s26
	v_lshl_add_u64 v[198:199], s[20:21], 0, v[128:129]
	ds_read_b128 v[166:169], v152 offset:32768
	ds_read_b128 v[170:173], v152 offset:33792
	ds_read_b128 v[174:177], v152 offset:34816
	ds_read_b128 v[178:181], v152 offset:35840
	ds_read_b128 v[182:185], v152 offset:36864
	ds_read_b128 v[186:189], v152 offset:37888
	ds_read_b128 v[190:193], v152 offset:38912
	ds_read_b128 v[194:197], v152 offset:39936
	global_load_lds_dwordx4 v[198:199], off
	v_lshl_add_u64 v[198:199], s[20:21], 0, v[132:133]
	s_mov_b32 m0, s27
	s_nop 0
	global_load_lds_dwordx4 v[198:199], off
	s_waitcnt lgkmcnt(0)
	s_barrier
	v_mfma_f32_16x16x32_f16 v[124:127], v[144:147], v[166:169], v[124:127]
	v_mfma_f32_16x16x32_f16 v[120:123], v[158:161], v[166:169], v[120:123]
	v_mfma_f32_16x16x32_f16 v[108:111], v[144:147], v[174:177], v[108:111]
	v_mfma_f32_16x16x32_f16 v[104:107], v[158:161], v[174:177], v[104:107]
	v_mfma_f32_16x16x32_f16 v[92:95], v[144:147], v[182:185], v[92:95]
	v_mfma_f32_16x16x32_f16 v[88:91], v[158:161], v[182:185], v[88:91]
	v_mfma_f32_16x16x32_f16 v[76:79], v[144:147], v[190:193], v[76:79]
	v_mfma_f32_16x16x32_f16 v[72:75], v[158:161], v[190:193], v[72:75]
	v_mfma_f32_16x16x32_f16 v[124:127], v[154:157], v[170:173], v[124:127]
	v_mfma_f32_16x16x32_f16 v[120:123], v[162:165], v[170:173], v[120:123]
	v_mfma_f32_16x16x32_f16 v[108:111], v[154:157], v[178:181], v[108:111]
	v_mfma_f32_16x16x32_f16 v[104:107], v[162:165], v[178:181], v[104:107]
	v_mfma_f32_16x16x32_f16 v[92:95], v[154:157], v[186:189], v[92:95]
	v_mfma_f32_16x16x32_f16 v[88:91], v[162:165], v[186:189], v[88:91]
	v_mfma_f32_16x16x32_f16 v[76:79], v[154:157], v[194:197], v[76:79]
	v_mfma_f32_16x16x32_f16 v[72:75], v[162:165], v[194:197], v[72:75]
	s_barrier
	s_add_i32 s20, 0, 0x1c000
	s_add_i32 s21, s79, s23
	v_add_u32_e32 v210, s20, v149
	v_lshl_add_u64 v[214:215], v[214:215], 0, s[0:1]
	s_mov_b32 m0, s21
	ds_read_b128 v[198:201], v210
	ds_read_b128 v[202:205], v210 offset:1024
	ds_read_b128 v[206:209], v210 offset:2048
	ds_read_b128 v[210:213], v210 offset:3072
	global_load_lds_dwordx4 v[214:215], off
	v_lshl_add_u64 v[214:215], v[216:217], 0, s[0:1]
	s_add_i32 m0, s21, 0x2000
	s_nop 0
	global_load_lds_dwordx4 v[214:215], off
	s_waitcnt lgkmcnt(0)
	s_barrier
	v_mfma_f32_16x16x32_f16 v[116:119], v[198:201], v[166:169], v[116:119]
	v_mfma_f32_16x16x32_f16 v[112:115], v[206:209], v[166:169], v[112:115]
	v_mfma_f32_16x16x32_f16 v[100:103], v[198:201], v[174:177], v[100:103]
	v_mfma_f32_16x16x32_f16 v[96:99], v[206:209], v[174:177], v[96:99]
	v_mfma_f32_16x16x32_f16 v[84:87], v[198:201], v[182:185], v[84:87]
	v_mfma_f32_16x16x32_f16 v[80:83], v[206:209], v[182:185], v[80:83]
	v_mfma_f32_16x16x32_f16 v[68:71], v[198:201], v[190:193], v[68:71]
	v_mfma_f32_16x16x32_f16 v[64:67], v[206:209], v[190:193], v[64:67]
	v_mfma_f32_16x16x32_f16 v[116:119], v[202:205], v[170:173], v[116:119]
	v_mfma_f32_16x16x32_f16 v[112:115], v[210:213], v[170:173], v[112:115]
	v_mfma_f32_16x16x32_f16 v[100:103], v[202:205], v[178:181], v[100:103]
	v_mfma_f32_16x16x32_f16 v[96:99], v[210:213], v[178:181], v[96:99]
	v_mfma_f32_16x16x32_f16 v[84:87], v[202:205], v[186:189], v[84:87]
	v_mfma_f32_16x16x32_f16 v[80:83], v[210:213], v[186:189], v[80:83]
	v_mfma_f32_16x16x32_f16 v[68:71], v[202:205], v[194:197], v[68:71]
	v_mfma_f32_16x16x32_f16 v[64:67], v[210:213], v[194:197], v[64:67]
	s_mov_b32 m0, s29
	v_lshl_add_u64 v[214:215], v[218:219], 0, s[0:1]
	s_barrier
	ds_read_b128 v[166:169], v152 offset:49152
	ds_read_b128 v[170:173], v152 offset:50176
	ds_read_b128 v[174:177], v152 offset:51200
	ds_read_b128 v[178:181], v152 offset:52224
	ds_read_b128 v[182:185], v152 offset:53248
	ds_read_b128 v[186:189], v152 offset:54272
	ds_read_b128 v[190:193], v152 offset:55296
	ds_read_b128 v[194:197], v152 offset:56320
	global_load_lds_dwordx4 v[214:215], off
	v_lshl_add_u64 v[214:215], v[220:221], 0, s[0:1]
	s_mov_b32 m0, s30
	s_nop 0
	global_load_lds_dwordx4 v[214:215], off
	s_waitcnt lgkmcnt(0)
	s_barrier
	v_mfma_f32_16x16x32_f16 v[60:63], v[144:147], v[166:169], v[60:63]
	v_mfma_f32_16x16x32_f16 v[56:59], v[158:161], v[166:169], v[56:59]
	v_mfma_f32_16x16x32_f16 v[44:47], v[144:147], v[174:177], v[44:47]
	v_mfma_f32_16x16x32_f16 v[40:43], v[158:161], v[174:177], v[40:43]
	v_mfma_f32_16x16x32_f16 v[28:31], v[144:147], v[182:185], v[28:31]
	v_mfma_f32_16x16x32_f16 v[24:27], v[158:161], v[182:185], v[24:27]
	v_mfma_f32_16x16x32_f16 v[12:15], v[144:147], v[190:193], v[12:15]
	v_mfma_f32_16x16x32_f16 v[8:11], v[158:161], v[190:193], v[8:11]
	v_mfma_f32_16x16x32_f16 v[60:63], v[154:157], v[170:173], v[60:63]
	v_mfma_f32_16x16x32_f16 v[56:59], v[162:165], v[170:173], v[56:59]
	v_mfma_f32_16x16x32_f16 v[44:47], v[154:157], v[178:181], v[44:47]
	v_mfma_f32_16x16x32_f16 v[40:43], v[162:165], v[178:181], v[40:43]
	v_mfma_f32_16x16x32_f16 v[28:31], v[154:157], v[186:189], v[28:31]
	v_mfma_f32_16x16x32_f16 v[24:27], v[162:165], v[186:189], v[24:27]
	v_mfma_f32_16x16x32_f16 v[12:15], v[154:157], v[194:197], v[12:15]
	v_mfma_f32_16x16x32_f16 v[8:11], v[162:165], v[194:197], v[8:11]
	s_barrier
	s_add_u32 s18, s18, 0x80080
	s_addc_u32 s19, s19, 0
	s_add_i32 s20, s20, s23
	v_lshl_add_u64 v[144:145], s[18:19], 0, v[130:131]
	s_mov_b32 m0, s20
	s_nop 0
	global_load_lds_dwordx4 v[144:145], off
	v_lshl_add_u64 v[144:145], s[18:19], 0, v[134:135]
	s_add_i32 m0, s20, 0x2000
	s_nop 0
	global_load_lds_dwordx4 v[144:145], off
	s_waitcnt vmcnt(6)
	s_barrier
	v_mfma_f32_16x16x32_f16 v[52:55], v[198:201], v[166:169], v[52:55]
	v_mfma_f32_16x16x32_f16 v[48:51], v[206:209], v[166:169], v[48:51]
	v_mfma_f32_16x16x32_f16 v[36:39], v[198:201], v[174:177], v[36:39]
	v_mfma_f32_16x16x32_f16 v[32:35], v[206:209], v[174:177], v[32:35]
	v_mfma_f32_16x16x32_f16 v[20:23], v[198:201], v[182:185], v[20:23]
	v_mfma_f32_16x16x32_f16 v[16:19], v[206:209], v[182:185], v[16:19]
	v_mfma_f32_16x16x32_f16 v[4:7], v[198:201], v[190:193], v[4:7]
	v_mfma_f32_16x16x32_f16 v[0:3], v[206:209], v[190:193], v[0:3]
	v_mfma_f32_16x16x32_f16 v[52:55], v[202:205], v[170:173], v[52:55]
	v_mfma_f32_16x16x32_f16 v[48:51], v[210:213], v[170:173], v[48:51]
	v_mfma_f32_16x16x32_f16 v[36:39], v[202:205], v[178:181], v[36:39]
	v_mfma_f32_16x16x32_f16 v[32:35], v[210:213], v[178:181], v[32:35]
	v_mfma_f32_16x16x32_f16 v[20:23], v[202:205], v[186:189], v[20:23]
	v_mfma_f32_16x16x32_f16 v[16:19], v[210:213], v[186:189], v[16:19]
	v_mfma_f32_16x16x32_f16 v[4:7], v[202:205], v[194:197], v[4:7]
	v_mfma_f32_16x16x32_f16 v[0:3], v[210:213], v[194:197], v[0:3]
	s_add_i32 s78, s78, 2
	s_add_u32 s16, s16, 0x100
	s_addc_u32 s17, s17, 0
	s_add_u32 s76, s76, 0x100
	s_addc_u32 s77, s77, 0
	s_cmp_gt_u32 s78, 29
	s_barrier
	s_cbranch_scc0 .LBB0_197
	s_setprio 0
	v_readlane_b32 s52, v254, 21
	v_readlane_b32 s54, v254, 23
	v_readlane_b32 s55, v254, 24
	v_lshl_add_u32 v154, s14, 8, v148
	v_lshl_or_b32 v144, s4, 8, v150
	v_mov_b64_e32 v[146:147], s[54:55]
	v_mad_i64_i32 v[146:147], s[4:5], v154, s70, v[146:147]
	v_cmp_gt_i32_e32 vcc, s71, v144
	v_ashrrev_i32_e32 v145, 31, v144
	v_readlane_b32 s53, v254, 22
	v_readlane_b32 s56, v254, 25
	v_readlane_b32 s57, v254, 26
	v_readlane_b32 s58, v254, 27
	v_readlane_b32 s59, v254, 28
	v_readlane_b32 s60, v254, 29
	v_readlane_b32 s61, v254, 30
	v_readlane_b32 s62, v254, 31
	v_readlane_b32 s63, v254, 32
	v_readlane_b32 s64, v254, 33
	v_readlane_b32 s65, v254, 34
	v_readlane_b32 s66, v254, 35
	v_readlane_b32 s67, v254, 36
	s_and_saveexec_b64 s[4:5], vcc
	s_cbranch_execz .LBB0_200
	v_cvt_pk_f16_f32 v123, v122, v123
	v_cvt_pk_f16_f32 v122, v120, v121
	v_cvt_pk_f16_f32 v121, v126, v127
	v_cvt_pk_f16_f32 v120, v124, v125
	v_lshl_add_u64 v[124:125], v[144:145], 1, v[146:147]
	global_store_dwordx4 v[124:125], v[120:123], off

.LBB0_647:
	ds_read_b128 v[80:83], v243
	ds_read_b128 v[88:91], v243 offset:1024
	ds_read_b128 v[96:99], v243 offset:2048
	ds_read_b128 v[100:103], v243 offset:3072
	s_add_u32 s18, s16, 0xfff80080
	s_addc_u32 s19, s17, -1
	s_cmp_eq_u32 s80, 28
	s_cselect_b32 s21, s9, s19
	s_cselect_b32 s20, s31, s18
	s_cselect_b32 s19, s7, s79
	s_cselect_b32 s18, s77, s78
	v_lshl_add_u64 v[176:177], s[16:17], 0, v[212:213]
	s_add_i32 m0, s15, 0xc000
	ds_read_b128 v[120:123], v244
	ds_read_b128 v[132:135], v244 offset:1024
	ds_read_b128 v[136:139], v244 offset:2048
	ds_read_b128 v[148:151], v244 offset:3072
	ds_read_b128 v[152:155], v244 offset:4096
	ds_read_b128 v[156:159], v244 offset:5120
	ds_read_b128 v[160:163], v244 offset:6144
	ds_read_b128 v[172:175], v244 offset:7168
	global_load_lds_dwordx4 v[176:177], off
	v_lshl_add_u64 v[176:177], s[16:17], 0, v[214:215]
	s_add_i32 m0, s15, 0xe000
	s_nop 0
	global_load_lds_dwordx4 v[176:177], off
	s_waitcnt lgkmcnt(0)
	s_barrier
	v_mfma_f32_16x16x32_f16 v[168:171], v[80:83], v[120:123], v[168:171]
	v_mfma_f32_16x16x32_f16 v[164:167], v[96:99], v[120:123], v[164:167]
	v_mfma_f32_16x16x32_f16 v[128:131], v[80:83], v[136:139], v[128:131]
	v_mfma_f32_16x16x32_f16 v[124:127], v[96:99], v[136:139], v[124:127]
	v_mfma_f32_16x16x32_f16 v[108:111], v[80:83], v[152:155], v[108:111]
	v_mfma_f32_16x16x32_f16 v[104:107], v[96:99], v[152:155], v[104:107]
	v_mfma_f32_16x16x32_f16 v[76:79], v[80:83], v[160:163], v[76:79]
	v_mfma_f32_16x16x32_f16 v[72:75], v[96:99], v[160:163], v[72:75]
	v_mfma_f32_16x16x32_f16 v[168:171], v[88:91], v[132:135], v[168:171]
	v_mfma_f32_16x16x32_f16 v[164:167], v[100:103], v[132:135], v[164:167]
	v_mfma_f32_16x16x32_f16 v[128:131], v[88:91], v[148:151], v[128:131]
	v_mfma_f32_16x16x32_f16 v[124:127], v[100:103], v[148:151], v[124:127]
	v_mfma_f32_16x16x32_f16 v[108:111], v[88:91], v[156:159], v[108:111]
	v_mfma_f32_16x16x32_f16 v[104:107], v[100:103], v[156:159], v[104:107]
	v_mfma_f32_16x16x32_f16 v[76:79], v[88:91], v[172:175], v[76:79]
	v_mfma_f32_16x16x32_f16 v[72:75], v[100:103], v[172:175], v[72:75]
	s_barrier
	s_add_i32 s81, s71, s24
	v_lshl_add_u64 v[196:197], s[18:19], 0, v[206:207]
	s_mov_b32 m0, s81
	ds_read_b128 v[176:179], v245
	ds_read_b128 v[180:183], v245 offset:1024
	ds_read_b128 v[184:187], v245 offset:2048
	ds_read_b128 v[188:191], v245 offset:3072
	global_load_lds_dwordx4 v[196:197], off
	v_lshl_add_u64 v[198:199], s[18:19], 0, v[210:211]
	s_add_i32 m0, s81, 0x2000
	s_nop 0
	global_load_lds_dwordx4 v[198:199], off
	s_waitcnt lgkmcnt(0)
	s_barrier
	v_mfma_f32_16x16x32_f16 v[144:147], v[176:179], v[120:123], v[144:147]
	v_mfma_f32_16x16x32_f16 v[116:119], v[176:179], v[136:139], v[116:119]
	v_mfma_f32_16x16x32_f16 v[112:115], v[184:187], v[136:139], v[112:115]
	v_mfma_f32_16x16x32_f16 v[92:95], v[176:179], v[152:155], v[92:95]
	v_mfma_f32_16x16x32_f16 v[84:87], v[184:187], v[152:155], v[84:87]
	v_mfma_f32_16x16x32_f16 v[68:71], v[176:179], v[160:163], v[68:71]
	v_mfma_f32_16x16x32_f16 v[64:67], v[184:187], v[160:163], v[64:67]
	v_mfma_f32_16x16x32_f16 v[144:147], v[180:183], v[132:135], v[144:147]
	v_mfma_f32_16x16x32_f16 v[120:123], v[184:187], v[120:123], v[140:143]
	v_mfma_f32_16x16x32_f16 v[116:119], v[180:183], v[148:151], v[116:119]
	v_mfma_f32_16x16x32_f16 v[112:115], v[188:191], v[148:151], v[112:115]
	v_mfma_f32_16x16x32_f16 v[92:95], v[180:183], v[156:159], v[92:95]
	v_mfma_f32_16x16x32_f16 v[84:87], v[188:191], v[156:159], v[84:87]
	v_mfma_f32_16x16x32_f16 v[68:71], v[180:183], v[172:175], v[68:71]
	v_mfma_f32_16x16x32_f16 v[64:67], v[188:191], v[172:175], v[64:67]
	v_mfma_f32_16x16x32_f16 v[120:123], v[188:191], v[132:135], v[120:123]
	s_mov_b32 m0, s15
	v_lshl_add_u64 v[200:201], s[20:21], 0, v[204:205]
	s_barrier
	ds_read_b128 v[132:135], v244 offset:16384
	ds_read_b128 v[136:139], v244 offset:17408
	ds_read_b128 v[140:143], v244 offset:18432
	ds_read_b128 v[148:151], v244 offset:19456
	ds_read_b128 v[152:155], v244 offset:20480
	ds_read_b128 v[156:159], v244 offset:21504
	ds_read_b128 v[160:163], v244 offset:22528
	ds_read_b128 v[172:175], v244 offset:23552
	global_load_lds_dwordx4 v[200:201], off
	v_lshl_add_u64 v[202:203], s[20:21], 0, v[208:209]
	s_mov_b32 m0, s25
	s_nop 0
	global_load_lds_dwordx4 v[202:203], off
	s_waitcnt lgkmcnt(0)
	s_barrier
	v_mfma_f32_16x16x32_f16 v[60:63], v[80:83], v[132:135], v[60:63]
	v_mfma_f32_16x16x32_f16 v[56:59], v[96:99], v[132:135], v[56:59]
	v_mfma_f32_16x16x32_f16 v[44:47], v[80:83], v[140:143], v[44:47]
	v_mfma_f32_16x16x32_f16 v[40:43], v[96:99], v[140:143], v[40:43]
	v_mfma_f32_16x16x32_f16 v[28:31], v[80:83], v[152:155], v[28:31]
	v_mfma_f32_16x16x32_f16 v[24:27], v[96:99], v[152:155], v[24:27]
	v_mfma_f32_16x16x32_f16 v[12:15], v[80:83], v[160:163], v[12:15]
	v_mfma_f32_16x16x32_f16 v[8:11], v[96:99], v[160:163], v[8:11]
	v_mfma_f32_16x16x32_f16 v[60:63], v[88:91], v[136:139], v[60:63]
	v_mfma_f32_16x16x32_f16 v[56:59], v[100:103], v[136:139], v[56:59]
	v_mfma_f32_16x16x32_f16 v[44:47], v[88:91], v[148:151], v[44:47]
	v_mfma_f32_16x16x32_f16 v[40:43], v[100:103], v[148:151], v[40:43]
	v_mfma_f32_16x16x32_f16 v[28:31], v[88:91], v[156:159], v[28:31]
	v_mfma_f32_16x16x32_f16 v[24:27], v[100:103], v[156:159], v[24:27]
	v_mfma_f32_16x16x32_f16 v[12:15], v[88:91], v[172:175], v[12:15]
	v_mfma_f32_16x16x32_f16 v[8:11], v[100:103], v[172:175], v[8:11]
	s_barrier
	s_add_u32 s82, s18, 0x80000
	s_addc_u32 s83, s19, 0
	s_add_i32 s81, s76, s24
	v_lshl_add_u64 v[80:81], s[82:83], 0, v[206:207]
	s_mov_b32 m0, s81
	s_nop 0
	global_load_lds_dwordx4 v[80:81], off
	v_lshl_add_u64 v[80:81], s[82:83], 0, v[210:211]
	s_add_i32 m0, s81, 0x2000
	s_nop 0
	global_load_lds_dwordx4 v[80:81], off
	s_waitcnt vmcnt(6)
	s_barrier
	v_mfma_f32_16x16x32_f16 v[52:55], v[176:179], v[132:135], v[52:55]
	v_mfma_f32_16x16x32_f16 v[48:51], v[184:187], v[132:135], v[48:51]
	v_mfma_f32_16x16x32_f16 v[36:39], v[176:179], v[140:143], v[36:39]
	v_mfma_f32_16x16x32_f16 v[32:35], v[184:187], v[140:143], v[32:35]
	v_mfma_f32_16x16x32_f16 v[20:23], v[176:179], v[152:155], v[20:23]
	v_mfma_f32_16x16x32_f16 v[16:19], v[184:187], v[152:155], v[16:19]
	v_mfma_f32_16x16x32_f16 v[4:7], v[176:179], v[160:163], v[4:7]
	v_mfma_f32_16x16x32_f16 v[0:3], v[184:187], v[160:163], v[0:3]
	v_mfma_f32_16x16x32_f16 v[52:55], v[180:183], v[136:139], v[52:55]
	v_mfma_f32_16x16x32_f16 v[48:51], v[188:191], v[136:139], v[48:51]
	v_mfma_f32_16x16x32_f16 v[36:39], v[180:183], v[148:151], v[36:39]
	v_mfma_f32_16x16x32_f16 v[32:35], v[188:191], v[148:151], v[32:35]
	v_mfma_f32_16x16x32_f16 v[20:23], v[180:183], v[156:159], v[20:23]
	v_mfma_f32_16x16x32_f16 v[16:19], v[188:191], v[156:159], v[16:19]
	v_mfma_f32_16x16x32_f16 v[4:7], v[180:183], v[172:175], v[4:7]
	v_mfma_f32_16x16x32_f16 v[0:3], v[188:191], v[172:175], v[0:3]
	s_add_i32 s81, 0, 0x18000
	v_add_u32_e32 v100, s81, v241
	s_barrier
	ds_read_b128 v[80:83], v100
	ds_read_b128 v[88:91], v100 offset:1024
	ds_read_b128 v[96:99], v100 offset:2048
	ds_read_b128 v[100:103], v100 offset:3072
	s_add_u32 s20, s20, 0x80000
	s_addc_u32 s21, s21, 0
	s_mov_b32 m0, s26
	v_lshl_add_u64 v[140:141], s[20:21], 0, v[204:205]
	ds_read_b128 v[132:135], v244 offset:32768
	ds_read_b128 v[136:139], v244 offset:33792
	ds_read_b128 v[148:151], v244 offset:34816
	ds_read_b128 v[152:155], v244 offset:35840
	ds_read_b128 v[156:159], v244 offset:36864
	ds_read_b128 v[160:163], v244 offset:37888
	ds_read_b128 v[172:175], v244 offset:38912
	ds_read_b128 v[176:179], v244 offset:39936
	global_load_lds_dwordx4 v[140:141], off
	v_lshl_add_u64 v[140:141], s[20:21], 0, v[208:209]
	s_mov_b32 m0, s27
	s_nop 0
	global_load_lds_dwordx4 v[140:141], off
	s_waitcnt lgkmcnt(0)
	s_barrier
	v_mfma_f32_16x16x32_f16 v[140:143], v[80:83], v[132:135], v[168:171]
	v_mfma_f32_16x16x32_f16 v[168:171], v[88:91], v[136:139], v[140:143]
	v_mfma_f32_16x16x32_f16 v[140:143], v[96:99], v[132:135], v[164:167]
	v_mfma_f32_16x16x32_f16 v[128:131], v[80:83], v[148:151], v[128:131]
	v_mfma_f32_16x16x32_f16 v[124:127], v[96:99], v[148:151], v[124:127]
	v_mfma_f32_16x16x32_f16 v[108:111], v[80:83], v[156:159], v[108:111]
	v_mfma_f32_16x16x32_f16 v[104:107], v[96:99], v[156:159], v[104:107]
	v_mfma_f32_16x16x32_f16 v[76:79], v[80:83], v[172:175], v[76:79]
	v_mfma_f32_16x16x32_f16 v[72:75], v[96:99], v[172:175], v[72:75]
	v_mfma_f32_16x16x32_f16 v[164:167], v[100:103], v[136:139], v[140:143]
	v_mfma_f32_16x16x32_f16 v[128:131], v[88:91], v[152:155], v[128:131]
	v_mfma_f32_16x16x32_f16 v[124:127], v[100:103], v[152:155], v[124:127]
	v_mfma_f32_16x16x32_f16 v[108:111], v[88:91], v[160:163], v[108:111]
	v_mfma_f32_16x16x32_f16 v[104:107], v[100:103], v[160:163], v[104:107]
	v_mfma_f32_16x16x32_f16 v[76:79], v[88:91], v[176:179], v[76:79]
	v_mfma_f32_16x16x32_f16 v[72:75], v[100:103], v[176:179], v[72:75]
	s_barrier
	s_add_i32 s20, 0, 0x1c000
	v_add_u32_e32 v140, s20, v241
	s_add_i32 s21, s81, s24
	ds_read_b128 v[180:183], v140
	ds_read_b128 v[184:187], v140 offset:1024
	ds_read_b128 v[188:191], v140 offset:2048
	ds_read_b128 v[192:195], v140 offset:3072
	v_lshl_add_u64 v[140:141], v[196:197], 0, s[4:5]
	s_mov_b32 m0, s21
	s_nop 0
	global_load_lds_dwordx4 v[140:141], off
	v_lshl_add_u64 v[140:141], v[198:199], 0, s[4:5]
	s_add_i32 m0, s21, 0x2000
	s_nop 0
	global_load_lds_dwordx4 v[140:141], off
	s_waitcnt lgkmcnt(0)
	s_barrier
	v_mfma_f32_16x16x32_f16 v[140:143], v[180:183], v[132:135], v[144:147]
	v_mfma_f32_16x16x32_f16 v[120:123], v[188:191], v[132:135], v[120:123]
	v_mfma_f32_16x16x32_f16 v[116:119], v[180:183], v[148:151], v[116:119]
	v_mfma_f32_16x16x32_f16 v[112:115], v[188:191], v[148:151], v[112:115]
	v_mfma_f32_16x16x32_f16 v[92:95], v[180:183], v[156:159], v[92:95]
	v_mfma_f32_16x16x32_f16 v[84:87], v[188:191], v[156:159], v[84:87]
	v_mfma_f32_16x16x32_f16 v[68:71], v[180:183], v[172:175], v[68:71]
	v_mfma_f32_16x16x32_f16 v[64:67], v[188:191], v[172:175], v[64:67]
	v_mfma_f32_16x16x32_f16 v[144:147], v[184:187], v[136:139], v[140:143]
	v_mfma_f32_16x16x32_f16 v[140:143], v[192:195], v[136:139], v[120:123]
	v_mfma_f32_16x16x32_f16 v[116:119], v[184:187], v[152:155], v[116:119]
	v_mfma_f32_16x16x32_f16 v[112:115], v[192:195], v[152:155], v[112:115]
	v_mfma_f32_16x16x32_f16 v[92:95], v[184:187], v[160:163], v[92:95]
	v_mfma_f32_16x16x32_f16 v[84:87], v[192:195], v[160:163], v[84:87]
	v_mfma_f32_16x16x32_f16 v[68:71], v[184:187], v[176:179], v[68:71]
	v_mfma_f32_16x16x32_f16 v[64:67], v[192:195], v[176:179], v[64:67]
	s_mov_b32 m0, s35
	v_lshl_add_u64 v[176:177], v[200:201], 0, s[4:5]
	s_barrier
	ds_read_b128 v[120:123], v244 offset:49152
	ds_read_b128 v[132:135], v244 offset:50176
	ds_read_b128 v[136:139], v244 offset:51200
	ds_read_b128 v[148:151], v244 offset:52224
	ds_read_b128 v[152:155], v244 offset:53248
	ds_read_b128 v[156:159], v244 offset:54272
	ds_read_b128 v[160:163], v244 offset:55296
	ds_read_b128 v[172:175], v244 offset:56320
	global_load_lds_dwordx4 v[176:177], off
	v_lshl_add_u64 v[176:177], v[202:203], 0, s[4:5]
	s_mov_b32 m0, s68
	s_nop 0
	global_load_lds_dwordx4 v[176:177], off
	s_waitcnt lgkmcnt(0)
	s_barrier
	v_mfma_f32_16x16x32_f16 v[60:63], v[80:83], v[120:123], v[60:63]
	v_mfma_f32_16x16x32_f16 v[56:59], v[96:99], v[120:123], v[56:59]
	v_mfma_f32_16x16x32_f16 v[44:47], v[80:83], v[136:139], v[44:47]
	v_mfma_f32_16x16x32_f16 v[40:43], v[96:99], v[136:139], v[40:43]
	v_mfma_f32_16x16x32_f16 v[28:31], v[80:83], v[152:155], v[28:31]
	v_mfma_f32_16x16x32_f16 v[24:27], v[96:99], v[152:155], v[24:27]
	v_mfma_f32_16x16x32_f16 v[12:15], v[80:83], v[160:163], v[12:15]
	v_mfma_f32_16x16x32_f16 v[8:11], v[96:99], v[160:163], v[8:11]
	v_mfma_f32_16x16x32_f16 v[60:63], v[88:91], v[132:135], v[60:63]
	v_mfma_f32_16x16x32_f16 v[56:59], v[100:103], v[132:135], v[56:59]
	v_mfma_f32_16x16x32_f16 v[44:47], v[88:91], v[148:151], v[44:47]
	v_mfma_f32_16x16x32_f16 v[40:43], v[100:103], v[148:151], v[40:43]
	v_mfma_f32_16x16x32_f16 v[28:31], v[88:91], v[156:159], v[28:31]
	v_mfma_f32_16x16x32_f16 v[24:27], v[100:103], v[156:159], v[24:27]
	v_mfma_f32_16x16x32_f16 v[12:15], v[88:91], v[172:175], v[12:15]
	v_mfma_f32_16x16x32_f16 v[8:11], v[100:103], v[172:175], v[8:11]
	s_barrier
	s_add_u32 s18, s18, 0x80080
	s_addc_u32 s19, s19, 0
	s_add_i32 s20, s20, s24
	v_lshl_add_u64 v[80:81], s[18:19], 0, v[206:207]
	s_mov_b32 m0, s20
	s_nop 0
	global_load_lds_dwordx4 v[80:81], off
	v_lshl_add_u64 v[80:81], s[18:19], 0, v[210:211]
	s_add_i32 m0, s20, 0x2000
	s_nop 0
	global_load_lds_dwordx4 v[80:81], off
	s_waitcnt vmcnt(6)
	s_barrier
	v_mfma_f32_16x16x32_f16 v[52:55], v[180:183], v[120:123], v[52:55]
	v_mfma_f32_16x16x32_f16 v[48:51], v[188:191], v[120:123], v[48:51]
	v_mfma_f32_16x16x32_f16 v[36:39], v[180:183], v[136:139], v[36:39]
	v_mfma_f32_16x16x32_f16 v[32:35], v[188:191], v[136:139], v[32:35]
	v_mfma_f32_16x16x32_f16 v[20:23], v[180:183], v[152:155], v[20:23]
	v_mfma_f32_16x16x32_f16 v[16:19], v[188:191], v[152:155], v[16:19]
	v_mfma_f32_16x16x32_f16 v[4:7], v[180:183], v[160:163], v[4:7]
	v_mfma_f32_16x16x32_f16 v[0:3], v[188:191], v[160:163], v[0:3]
	v_mfma_f32_16x16x32_f16 v[52:55], v[184:187], v[132:135], v[52:55]
	v_mfma_f32_16x16x32_f16 v[48:51], v[192:195], v[132:135], v[48:51]
	v_mfma_f32_16x16x32_f16 v[36:39], v[184:187], v[148:151], v[36:39]
	v_mfma_f32_16x16x32_f16 v[32:35], v[192:195], v[148:151], v[32:35]
	v_mfma_f32_16x16x32_f16 v[20:23], v[184:187], v[156:159], v[20:23]
	v_mfma_f32_16x16x32_f16 v[16:19], v[192:195], v[156:159], v[16:19]
	v_mfma_f32_16x16x32_f16 v[4:7], v[184:187], v[172:175], v[4:7]
	v_mfma_f32_16x16x32_f16 v[0:3], v[192:195], v[172:175], v[0:3]
	s_add_i32 s80, s80, 2
	s_add_u32 s16, s16, 0x100
	s_addc_u32 s17, s17, 0
	s_add_u32 s78, s78, 0x100
	s_addc_u32 s79, s79, 0
	s_cmp_gt_u32 s80, 29
	s_barrier
	s_cbranch_scc0 .LBB0_647
	s_setprio 0
	s_lshl_b32 s7, s14, 8
	s_add_i32 s9, s7, 0xffffe000
	s_lshr_b32 s9, s9, 11
	s_mulk_i32 s9, 0x1800
	s_addk_i32 s9, 0x1800
	s_cmp_gt_i32 s14, 31
	s_cselect_b32 s16, s9, 0
	s_ashr_i32 s17, s16, 31
	v_lshl_or_b32 v120, s30, 8, v242
	s_lshl_b64 s[16:17], s[16:17], 2
	s_add_u32 s16, s29, s16
	v_ashrrev_i32_e32 v121, 31, v120
	v_add_u32_e32 v122, s7, v240
	s_addc_u32 s17, s34, s17
	v_lshlrev_b64 v[220:221], 1, v[120:121]
	v_ashrrev_i32_e32 v123, 31, v122
	v_lshl_add_u64 v[88:89], v[120:121], 2, s[16:17]
	v_lshl_add_u64 v[120:121], s[40:41], 0, v[220:221]
	v_lshlrev_b64 v[236:237], 12, v[122:123]
	v_lshl_add_u64 v[132:133], v[120:121], 0, v[236:237]
	global_load_dwordx4 v[96:99], v[88:89], off offset:16
	global_load_dwordx4 v[100:103], v[88:89], off
	global_load_dwordx4 v[80:83], v[88:89], off offset:528
	s_nop 0
	global_load_dwordx4 v[88:91], v[88:89], off offset:512
	s_nop 0
	global_load_dwordx4 v[246:249], v[132:133], off nt
	global_load_dwordx4 v[200:203], v[132:133], off offset:256 nt
	v_or_b32_e32 v132, 16, v122
	v_ashrrev_i32_e32 v133, 31, v132
	v_lshlrev_b64 v[234:235], 12, v[132:133]
	v_lshl_add_u64 v[132:133], v[120:121], 0, v[234:235]
	global_load_dwordx4 v[196:199], v[132:133], off nt
	global_load_dwordx4 v[192:195], v[132:133], off offset:256 nt
	v_or_b32_e32 v132, 32, v122
	v_ashrrev_i32_e32 v133, 31, v132
	v_lshlrev_b64 v[232:233], 12, v[132:133]
	v_lshl_add_u64 v[132:133], v[120:121], 0, v[232:233]
	global_load_dwordx4 v[188:191], v[132:133], off nt
	global_load_dwordx4 v[184:187], v[132:133], off offset:256 nt
	v_or_b32_e32 v122, 48, v122
	v_ashrrev_i32_e32 v123, 31, v122
	v_lshlrev_b64 v[230:231], 12, v[122:123]
	v_lshl_add_u64 v[122:123], v[120:121], 0, v[230:231]
	global_load_dwordx4 v[180:183], v[122:123], off nt
	global_load_dwordx4 v[176:179], v[122:123], off offset:256 nt
	s_mov_b64 s[16:17], 0x80000
	v_lshl_add_u64 v[228:229], v[236:237], 0, s[16:17]
	v_lshl_add_u64 v[122:123], v[120:121], 0, v[228:229]
	global_load_dwordx4 v[172:175], v[122:123], off nt
	global_load_dwordx4 v[160:163], v[122:123], off offset:256 nt
	s_mov_b64 s[16:17], 0x90000
	v_lshl_add_u64 v[226:227], v[236:237], 0, s[16:17]
	v_lshl_add_u64 v[122:123], v[120:121], 0, v[226:227]
	global_load_dwordx4 v[156:159], v[122:123], off nt
	global_load_dwordx4 v[152:155], v[122:123], off offset:256 nt
	s_mov_b64 s[16:17], 0xa0000
	v_lshl_add_u64 v[224:225], v[236:237], 0, s[16:17]
	v_lshl_add_u64 v[122:123], v[120:121], 0, v[224:225]
	global_load_dwordx4 v[148:151], v[122:123], off nt
	global_load_dwordx4 v[136:139], v[122:123], off offset:256 nt
	s_mov_b64 s[16:17], 0xb0000
	v_lshl_add_u64 v[222:223], v[236:237], 0, s[16:17]
	v_lshl_add_u64 v[120:121], v[120:121], 0, v[222:223]
	global_load_dwordx4 v[132:135], v[120:121], off nt
	s_nop 0
	global_load_dwordx4 v[120:123], v[120:121], off offset:256 nt
	s_and_b64 vcc, exec, s[2:3]
	s_mov_b32 s30, s6
	s_mov_b32 s14, s8
	s_mov_b64 s[18:19], s[12:13]
	s_mov_b64 s[16:17], s[10:11]
	s_waitcnt vmcnt(0)
	v_cvt_f32_f16_e32 v250, v246
	v_cvt_f32_f16_sdwa v251, v246 dst_sel:DWORD dst_unused:UNUSED_PAD src0_sel:WORD_1
	v_pk_fma_f32 v[168:169], v[168:169], v[100:101], v[250:251]
	s_nop 0
	v_cvt_pk_f16_f32 v246, v168, v169
	v_cvt_f32_f16_e32 v168, v248
	v_cvt_f32_f16_sdwa v169, v248 dst_sel:DWORD dst_unused:UNUSED_PAD src0_sel:WORD_1
	v_pk_fma_f32 v[164:165], v[164:165], v[96:97], v[168:169]
	s_nop 0
	v_cvt_pk_f16_f32 v248, v164, v165
	v_cvt_f32_f16_e32 v164, v247
	v_cvt_f32_f16_sdwa v165, v247 dst_sel:DWORD dst_unused:UNUSED_PAD src0_sel:WORD_1
	v_pk_fma_f32 v[164:165], v[170:171], v[102:103], v[164:165]
	s_nop 0
	v_cvt_pk_f16_f32 v247, v164, v165
	v_cvt_f32_f16_e32 v164, v249
	v_cvt_f32_f16_sdwa v165, v249 dst_sel:DWORD dst_unused:UNUSED_PAD src0_sel:WORD_1
	v_pk_fma_f32 v[164:165], v[166:167], v[98:99], v[164:165]
	s_nop 0
	v_cvt_pk_f16_f32 v249, v164, v165
	v_lshl_add_u64 v[164:165], s[0:1], 0, v[236:237]
	v_lshl_add_u64 v[168:169], v[164:165], 0, v[220:221]
	v_cvt_f32_f16_e32 v164, v200
	v_cvt_f32_f16_sdwa v165, v200 dst_sel:DWORD dst_unused:UNUSED_PAD src0_sel:WORD_1
	global_store_dwordx4 v[168:169], v[246:249], off
	v_pk_fma_f32 v[144:145], v[144:145], v[88:89], v[164:165]
	s_nop 0
	v_cvt_pk_f16_f32 v164, v144, v145
	v_cvt_f32_f16_e32 v144, v202
	v_cvt_f32_f16_sdwa v145, v202 dst_sel:DWORD dst_unused:UNUSED_PAD src0_sel:WORD_1
	v_pk_fma_f32 v[140:141], v[140:141], v[80:81], v[144:145]
	s_nop 0
	v_cvt_pk_f16_f32 v166, v140, v141
	v_cvt_f32_f16_e32 v140, v201
	v_cvt_f32_f16_sdwa v141, v201 dst_sel:DWORD dst_unused:UNUSED_PAD src0_sel:WORD_1
	v_pk_fma_f32 v[140:141], v[146:147], v[90:91], v[140:141]
	s_nop 0
	v_cvt_pk_f16_f32 v165, v140, v141
	v_cvt_f32_f16_e32 v140, v203
	v_cvt_f32_f16_sdwa v141, v203 dst_sel:DWORD dst_unused:UNUSED_PAD src0_sel:WORD_1
	v_pk_fma_f32 v[140:141], v[142:143], v[82:83], v[140:141]
	s_nop 0
	v_cvt_pk_f16_f32 v167, v140, v141
	v_cvt_f32_f16_e32 v140, v196
	v_cvt_f32_f16_sdwa v141, v196 dst_sel:DWORD dst_unused:UNUSED_PAD src0_sel:WORD_1
	global_store_dwordx4 v[168:169], v[164:167], off offset:256
	v_pk_fma_f32 v[128:129], v[128:129], v[100:101], v[140:141]
	s_nop 0
	v_cvt_pk_f16_f32 v140, v128, v129
	v_cvt_f32_f16_e32 v128, v198
	v_cvt_f32_f16_sdwa v129, v198 dst_sel:DWORD dst_unused:UNUSED_PAD src0_sel:WORD_1
	v_pk_fma_f32 v[124:125], v[124:125], v[96:97], v[128:129]
	s_nop 0
	v_cvt_pk_f16_f32 v142, v124, v125
	v_cvt_f32_f16_e32 v124, v197
	v_cvt_f32_f16_sdwa v125, v197 dst_sel:DWORD dst_unused:UNUSED_PAD src0_sel:WORD_1
	v_pk_fma_f32 v[124:125], v[130:131], v[102:103], v[124:125]
	s_nop 0
	v_cvt_pk_f16_f32 v141, v124, v125
	v_cvt_f32_f16_e32 v124, v199
	v_cvt_f32_f16_sdwa v125, v199 dst_sel:DWORD dst_unused:UNUSED_PAD src0_sel:WORD_1
	v_pk_fma_f32 v[124:125], v[126:127], v[98:99], v[124:125]
	s_nop 0
	v_cvt_pk_f16_f32 v143, v124, v125
	v_lshl_add_u64 v[124:125], s[0:1], 0, v[234:235]
	v_lshl_add_u64 v[128:129], v[124:125], 0, v[220:221]
	v_cvt_f32_f16_e32 v124, v192
	v_cvt_f32_f16_sdwa v125, v192 dst_sel:DWORD dst_unused:UNUSED_PAD src0_sel:WORD_1
	global_store_dwordx4 v[128:129], v[140:143], off
	v_pk_fma_f32 v[116:117], v[116:117], v[88:89], v[124:125]
	s_nop 0
	v_cvt_pk_f16_f32 v124, v116, v117
	v_cvt_f32_f16_e32 v116, v194
	v_cvt_f32_f16_sdwa v117, v194 dst_sel:DWORD dst_unused:UNUSED_PAD src0_sel:WORD_1
	v_pk_fma_f32 v[112:113], v[112:113], v[80:81], v[116:117]
	s_nop 0
	v_cvt_pk_f16_f32 v126, v112, v113
	v_cvt_f32_f16_e32 v112, v193
	v_cvt_f32_f16_sdwa v113, v193 dst_sel:DWORD dst_unused:UNUSED_PAD src0_sel:WORD_1
	v_pk_fma_f32 v[112:113], v[118:119], v[90:91], v[112:113]
	s_nop 0
	v_cvt_pk_f16_f32 v125, v112, v113
	v_cvt_f32_f16_e32 v112, v195
	v_cvt_f32_f16_sdwa v113, v195 dst_sel:DWORD dst_unused:UNUSED_PAD src0_sel:WORD_1
	v_pk_fma_f32 v[112:113], v[114:115], v[82:83], v[112:113]
	s_nop 0
	v_cvt_pk_f16_f32 v127, v112, v113
	v_cvt_f32_f16_e32 v112, v188
	v_cvt_f32_f16_sdwa v113, v188 dst_sel:DWORD dst_unused:UNUSED_PAD src0_sel:WORD_1
	global_store_dwordx4 v[128:129], v[124:127], off offset:256
	v_pk_fma_f32 v[108:109], v[108:109], v[100:101], v[112:113]
	s_nop 0
	v_cvt_pk_f16_f32 v112, v108, v109
	v_cvt_f32_f16_e32 v108, v190
	v_cvt_f32_f16_sdwa v109, v190 dst_sel:DWORD dst_unused:UNUSED_PAD src0_sel:WORD_1
	v_pk_fma_f32 v[104:105], v[104:105], v[96:97], v[108:109]
	s_nop 0
	v_cvt_pk_f16_f32 v114, v104, v105
	v_cvt_f32_f16_e32 v104, v189
	v_cvt_f32_f16_sdwa v105, v189 dst_sel:DWORD dst_unused:UNUSED_PAD src0_sel:WORD_1
	v_pk_fma_f32 v[104:105], v[110:111], v[102:103], v[104:105]
	s_nop 0
	v_cvt_pk_f16_f32 v113, v104, v105
	v_cvt_f32_f16_e32 v104, v191
	v_cvt_f32_f16_sdwa v105, v191 dst_sel:DWORD dst_unused:UNUSED_PAD src0_sel:WORD_1
	v_pk_fma_f32 v[104:105], v[106:107], v[98:99], v[104:105]
	s_nop 0
	v_cvt_pk_f16_f32 v115, v104, v105
	v_lshl_add_u64 v[104:105], s[0:1], 0, v[232:233]
	v_lshl_add_u64 v[108:109], v[104:105], 0, v[220:221]
	v_cvt_f32_f16_e32 v104, v184
	v_cvt_f32_f16_sdwa v105, v184 dst_sel:DWORD dst_unused:UNUSED_PAD src0_sel:WORD_1
	global_store_dwordx4 v[108:109], v[112:115], off
	v_pk_fma_f32 v[92:93], v[92:93], v[88:89], v[104:105]
	s_nop 0
	v_cvt_pk_f16_f32 v104, v92, v93
	v_cvt_f32_f16_e32 v92, v186
	v_cvt_f32_f16_sdwa v93, v186 dst_sel:DWORD dst_unused:UNUSED_PAD src0_sel:WORD_1
	v_pk_fma_f32 v[84:85], v[84:85], v[80:81], v[92:93]
	s_nop 0
	v_cvt_pk_f16_f32 v106, v84, v85
	v_cvt_f32_f16_e32 v84, v185
	v_cvt_f32_f16_sdwa v85, v185 dst_sel:DWORD dst_unused:UNUSED_PAD src0_sel:WORD_1
	v_pk_fma_f32 v[84:85], v[94:95], v[90:91], v[84:85]
	s_nop 0
	v_cvt_pk_f16_f32 v105, v84, v85
	v_cvt_f32_f16_e32 v84, v187
	v_cvt_f32_f16_sdwa v85, v187 dst_sel:DWORD dst_unused:UNUSED_PAD src0_sel:WORD_1
	v_pk_fma_f32 v[84:85], v[86:87], v[82:83], v[84:85]
	s_nop 0
	v_cvt_pk_f16_f32 v107, v84, v85
	v_cvt_f32_f16_e32 v84, v180
	v_cvt_f32_f16_sdwa v85, v180 dst_sel:DWORD dst_unused:UNUSED_PAD src0_sel:WORD_1
	global_store_dwordx4 v[108:109], v[104:107], off offset:256
	v_pk_fma_f32 v[76:77], v[76:77], v[100:101], v[84:85]
	s_nop 0
	v_cvt_pk_f16_f32 v84, v76, v77
	v_cvt_f32_f16_e32 v76, v182
	v_cvt_f32_f16_sdwa v77, v182 dst_sel:DWORD dst_unused:UNUSED_PAD src0_sel:WORD_1
	v_pk_fma_f32 v[72:73], v[72:73], v[96:97], v[76:77]
	s_nop 0
	v_cvt_pk_f16_f32 v86, v72, v73
	v_cvt_f32_f16_e32 v72, v181
	v_cvt_f32_f16_sdwa v73, v181 dst_sel:DWORD dst_unused:UNUSED_PAD src0_sel:WORD_1
	v_pk_fma_f32 v[72:73], v[78:79], v[102:103], v[72:73]
	s_nop 0
	v_cvt_pk_f16_f32 v85, v72, v73
	v_cvt_f32_f16_e32 v72, v183
	v_cvt_f32_f16_sdwa v73, v183 dst_sel:DWORD dst_unused:UNUSED_PAD src0_sel:WORD_1
	v_pk_fma_f32 v[72:73], v[74:75], v[98:99], v[72:73]
	s_nop 0
	v_cvt_pk_f16_f32 v87, v72, v73
	v_lshl_add_u64 v[72:73], s[0:1], 0, v[230:231]
	v_lshl_add_u64 v[76:77], v[72:73], 0, v[220:221]
	v_cvt_f32_f16_e32 v72, v176
	v_cvt_f32_f16_sdwa v73, v176 dst_sel:DWORD dst_unused:UNUSED_PAD src0_sel:WORD_1
	global_store_dwordx4 v[76:77], v[84:87], off
	v_pk_fma_f32 v[68:69], v[68:69], v[88:89], v[72:73]
	s_nop 0
	v_cvt_pk_f16_f32 v72, v68, v69
	v_cvt_f32_f16_e32 v68, v178
	v_cvt_f32_f16_sdwa v69, v178 dst_sel:DWORD dst_unused:UNUSED_PAD src0_sel:WORD_1
	v_pk_fma_f32 v[64:65], v[64:65], v[80:81], v[68:69]
	s_nop 0
	v_cvt_pk_f16_f32 v74, v64, v65
	v_cvt_f32_f16_e32 v64, v177
	v_cvt_f32_f16_sdwa v65, v177 dst_sel:DWORD dst_unused:UNUSED_PAD src0_sel:WORD_1
	v_pk_fma_f32 v[64:65], v[70:71], v[90:91], v[64:65]
	s_nop 0
	v_cvt_pk_f16_f32 v73, v64, v65
	v_cvt_f32_f16_e32 v64, v179
	v_cvt_f32_f16_sdwa v65, v179 dst_sel:DWORD dst_unused:UNUSED_PAD src0_sel:WORD_1
	v_pk_fma_f32 v[64:65], v[66:67], v[82:83], v[64:65]
	s_nop 0
	v_cvt_pk_f16_f32 v75, v64, v65
	v_cvt_f32_f16_e32 v64, v172
	v_cvt_f32_f16_sdwa v65, v172 dst_sel:DWORD dst_unused:UNUSED_PAD src0_sel:WORD_1
	global_store_dwordx4 v[76:77], v[72:75], off offset:256
	v_pk_fma_f32 v[60:61], v[60:61], v[100:101], v[64:65]
	s_nop 0
	v_cvt_pk_f16_f32 v64, v60, v61
	v_cvt_f32_f16_e32 v60, v174
	v_cvt_f32_f16_sdwa v61, v174 dst_sel:DWORD dst_unused:UNUSED_PAD src0_sel:WORD_1
	v_pk_fma_f32 v[56:57], v[56:57], v[96:97], v[60:61]
	s_nop 0
	v_cvt_pk_f16_f32 v66, v56, v57
	v_cvt_f32_f16_e32 v56, v173
	v_cvt_f32_f16_sdwa v57, v173 dst_sel:DWORD dst_unused:UNUSED_PAD src0_sel:WORD_1
	v_pk_fma_f32 v[56:57], v[62:63], v[102:103], v[56:57]
	s_nop 0
	v_cvt_pk_f16_f32 v65, v56, v57
	v_cvt_f32_f16_e32 v56, v175
	v_cvt_f32_f16_sdwa v57, v175 dst_sel:DWORD dst_unused:UNUSED_PAD src0_sel:WORD_1
	v_pk_fma_f32 v[56:57], v[58:59], v[98:99], v[56:57]
	s_nop 0
	v_cvt_pk_f16_f32 v67, v56, v57
	v_lshl_add_u64 v[56:57], s[0:1], 0, v[228:229]
	v_lshl_add_u64 v[60:61], v[56:57], 0, v[220:221]
	v_cvt_f32_f16_e32 v56, v160
	v_cvt_f32_f16_sdwa v57, v160 dst_sel:DWORD dst_unused:UNUSED_PAD src0_sel:WORD_1
	global_store_dwordx4 v[60:61], v[64:67], off
	v_pk_fma_f32 v[52:53], v[52:53], v[88:89], v[56:57]
	s_nop 0
	v_cvt_pk_f16_f32 v56, v52, v53
	v_cvt_f32_f16_e32 v52, v162
	v_cvt_f32_f16_sdwa v53, v162 dst_sel:DWORD dst_unused:UNUSED_PAD src0_sel:WORD_1
	v_pk_fma_f32 v[48:49], v[48:49], v[80:81], v[52:53]
	s_nop 0
	v_cvt_pk_f16_f32 v58, v48, v49
	v_cvt_f32_f16_e32 v48, v161
	v_cvt_f32_f16_sdwa v49, v161 dst_sel:DWORD dst_unused:UNUSED_PAD src0_sel:WORD_1
	v_pk_fma_f32 v[48:49], v[54:55], v[90:91], v[48:49]
	s_nop 0
	v_cvt_pk_f16_f32 v57, v48, v49
	v_cvt_f32_f16_e32 v48, v163
	v_cvt_f32_f16_sdwa v49, v163 dst_sel:DWORD dst_unused:UNUSED_PAD src0_sel:WORD_1
	v_pk_fma_f32 v[48:49], v[50:51], v[82:83], v[48:49]
	s_nop 0
	v_cvt_pk_f16_f32 v59, v48, v49
	v_cvt_f32_f16_e32 v48, v156
	v_cvt_f32_f16_sdwa v49, v156 dst_sel:DWORD dst_unused:UNUSED_PAD src0_sel:WORD_1
	global_store_dwordx4 v[60:61], v[56:59], off offset:256
	v_pk_fma_f32 v[44:45], v[44:45], v[100:101], v[48:49]
	s_nop 0
	v_cvt_pk_f16_f32 v48, v44, v45
	v_cvt_f32_f16_e32 v44, v158
	v_cvt_f32_f16_sdwa v45, v158 dst_sel:DWORD dst_unused:UNUSED_PAD src0_sel:WORD_1
	v_pk_fma_f32 v[40:41], v[40:41], v[96:97], v[44:45]
	s_nop 0
	v_cvt_pk_f16_f32 v50, v40, v41
	v_cvt_f32_f16_e32 v40, v157
	v_cvt_f32_f16_sdwa v41, v157 dst_sel:DWORD dst_unused:UNUSED_PAD src0_sel:WORD_1
	v_pk_fma_f32 v[40:41], v[46:47], v[102:103], v[40:41]
	s_nop 0
	v_cvt_pk_f16_f32 v49, v40, v41
	v_cvt_f32_f16_e32 v40, v159
	v_cvt_f32_f16_sdwa v41, v159 dst_sel:DWORD dst_unused:UNUSED_PAD src0_sel:WORD_1
	v_pk_fma_f32 v[40:41], v[42:43], v[98:99], v[40:41]
	s_nop 0
	v_cvt_pk_f16_f32 v51, v40, v41
	v_lshl_add_u64 v[40:41], s[0:1], 0, v[226:227]
	v_lshl_add_u64 v[44:45], v[40:41], 0, v[220:221]
	v_cvt_f32_f16_e32 v40, v152
	v_cvt_f32_f16_sdwa v41, v152 dst_sel:DWORD dst_unused:UNUSED_PAD src0_sel:WORD_1
	global_store_dwordx4 v[44:45], v[48:51], off
	v_pk_fma_f32 v[36:37], v[36:37], v[88:89], v[40:41]
	s_nop 0
	v_cvt_pk_f16_f32 v40, v36, v37
	v_cvt_f32_f16_e32 v36, v154
	v_cvt_f32_f16_sdwa v37, v154 dst_sel:DWORD dst_unused:UNUSED_PAD src0_sel:WORD_1
	v_pk_fma_f32 v[32:33], v[32:33], v[80:81], v[36:37]
	s_nop 0
	v_cvt_pk_f16_f32 v42, v32, v33
	v_cvt_f32_f16_e32 v32, v153
	v_cvt_f32_f16_sdwa v33, v153 dst_sel:DWORD dst_unused:UNUSED_PAD src0_sel:WORD_1
	v_pk_fma_f32 v[32:33], v[38:39], v[90:91], v[32:33]
	s_nop 0
	v_cvt_pk_f16_f32 v41, v32, v33
	v_cvt_f32_f16_e32 v32, v155
	v_cvt_f32_f16_sdwa v33, v155 dst_sel:DWORD dst_unused:UNUSED_PAD src0_sel:WORD_1
	v_pk_fma_f32 v[32:33], v[34:35], v[82:83], v[32:33]
	s_nop 0
	v_cvt_pk_f16_f32 v43, v32, v33
	v_cvt_f32_f16_e32 v32, v148
	v_cvt_f32_f16_sdwa v33, v148 dst_sel:DWORD dst_unused:UNUSED_PAD src0_sel:WORD_1
	global_store_dwordx4 v[44:45], v[40:43], off offset:256
	v_pk_fma_f32 v[28:29], v[28:29], v[100:101], v[32:33]
	s_nop 0
	v_cvt_pk_f16_f32 v32, v28, v29
	v_cvt_f32_f16_e32 v28, v150
	v_cvt_f32_f16_sdwa v29, v150 dst_sel:DWORD dst_unused:UNUSED_PAD src0_sel:WORD_1
	v_pk_fma_f32 v[24:25], v[24:25], v[96:97], v[28:29]
	s_nop 0
	v_cvt_pk_f16_f32 v34, v24, v25
	v_cvt_f32_f16_e32 v24, v149
	v_cvt_f32_f16_sdwa v25, v149 dst_sel:DWORD dst_unused:UNUSED_PAD src0_sel:WORD_1
	v_pk_fma_f32 v[24:25], v[30:31], v[102:103], v[24:25]
	s_nop 0
	v_cvt_pk_f16_f32 v33, v24, v25
	v_cvt_f32_f16_e32 v24, v151
	v_cvt_f32_f16_sdwa v25, v151 dst_sel:DWORD dst_unused:UNUSED_PAD src0_sel:WORD_1
	v_pk_fma_f32 v[24:25], v[26:27], v[98:99], v[24:25]
	s_nop 0
	v_cvt_pk_f16_f32 v35, v24, v25
	v_lshl_add_u64 v[24:25], s[0:1], 0, v[224:225]
	v_lshl_add_u64 v[28:29], v[24:25], 0, v[220:221]
	v_cvt_f32_f16_e32 v24, v136
	v_cvt_f32_f16_sdwa v25, v136 dst_sel:DWORD dst_unused:UNUSED_PAD src0_sel:WORD_1
	global_store_dwordx4 v[28:29], v[32:35], off
	v_pk_fma_f32 v[20:21], v[20:21], v[88:89], v[24:25]
	s_nop 0
	v_cvt_pk_f16_f32 v24, v20, v21
	v_cvt_f32_f16_e32 v20, v138
	v_cvt_f32_f16_sdwa v21, v138 dst_sel:DWORD dst_unused:UNUSED_PAD src0_sel:WORD_1
	v_pk_fma_f32 v[16:17], v[16:17], v[80:81], v[20:21]
	s_nop 0
	v_cvt_pk_f16_f32 v26, v16, v17
	v_cvt_f32_f16_e32 v16, v137
	v_cvt_f32_f16_sdwa v17, v137 dst_sel:DWORD dst_unused:UNUSED_PAD src0_sel:WORD_1
	v_pk_fma_f32 v[16:17], v[22:23], v[90:91], v[16:17]
	s_nop 0
	v_cvt_pk_f16_f32 v25, v16, v17
	v_cvt_f32_f16_e32 v16, v139
	v_cvt_f32_f16_sdwa v17, v139 dst_sel:DWORD dst_unused:UNUSED_PAD src0_sel:WORD_1
	v_pk_fma_f32 v[16:17], v[18:19], v[82:83], v[16:17]
	s_nop 0
	v_cvt_pk_f16_f32 v27, v16, v17
	v_cvt_f32_f16_e32 v16, v132
	v_cvt_f32_f16_sdwa v17, v132 dst_sel:DWORD dst_unused:UNUSED_PAD src0_sel:WORD_1
	global_store_dwordx4 v[28:29], v[24:27], off offset:256
	v_pk_fma_f32 v[12:13], v[12:13], v[100:101], v[16:17]
	s_nop 0
	v_cvt_pk_f16_f32 v16, v12, v13
	v_cvt_f32_f16_e32 v12, v134
	v_cvt_f32_f16_sdwa v13, v134 dst_sel:DWORD dst_unused:UNUSED_PAD src0_sel:WORD_1
	v_pk_fma_f32 v[8:9], v[8:9], v[96:97], v[12:13]
	s_nop 0
	v_cvt_pk_f16_f32 v18, v8, v9
	v_cvt_f32_f16_e32 v8, v133
	v_cvt_f32_f16_sdwa v9, v133 dst_sel:DWORD dst_unused:UNUSED_PAD src0_sel:WORD_1
	v_pk_fma_f32 v[8:9], v[14:15], v[102:103], v[8:9]
	s_nop 0
	v_cvt_pk_f16_f32 v17, v8, v9
	v_cvt_f32_f16_e32 v8, v135
	v_cvt_f32_f16_sdwa v9, v135 dst_sel:DWORD dst_unused:UNUSED_PAD src0_sel:WORD_1
	v_pk_fma_f32 v[8:9], v[10:11], v[98:99], v[8:9]
	s_nop 0
	v_cvt_pk_f16_f32 v19, v8, v9
	v_lshl_add_u64 v[8:9], s[0:1], 0, v[222:223]
	v_lshl_add_u64 v[12:13], v[8:9], 0, v[220:221]
	v_cvt_f32_f16_e32 v8, v120
	v_cvt_f32_f16_sdwa v9, v120 dst_sel:DWORD dst_unused:UNUSED_PAD src0_sel:WORD_1
	global_store_dwordx4 v[12:13], v[16:19], off
	v_pk_fma_f32 v[4:5], v[4:5], v[88:89], v[8:9]
	s_nop 0
	v_cvt_pk_f16_f32 v8, v4, v5
	v_cvt_f32_f16_e32 v4, v122
	v_cvt_f32_f16_sdwa v5, v122 dst_sel:DWORD dst_unused:UNUSED_PAD src0_sel:WORD_1
	v_pk_fma_f32 v[0:1], v[0:1], v[80:81], v[4:5]
	s_nop 0
	v_cvt_pk_f16_f32 v10, v0, v1
	v_cvt_f32_f16_e32 v0, v121
	v_cvt_f32_f16_sdwa v1, v121 dst_sel:DWORD dst_unused:UNUSED_PAD src0_sel:WORD_1
	v_pk_fma_f32 v[0:1], v[6:7], v[90:91], v[0:1]
	s_nop 0
	v_cvt_pk_f16_f32 v9, v0, v1
	v_cvt_f32_f16_e32 v0, v123
	v_cvt_f32_f16_sdwa v1, v123 dst_sel:DWORD dst_unused:UNUSED_PAD src0_sel:WORD_1
	v_pk_fma_f32 v[0:1], v[2:3], v[82:83], v[0:1]
	s_nop 0
	v_cvt_pk_f16_f32 v11, v0, v1
	global_store_dwordx4 v[12:13], v[8:11], off offset:256
	s_cbranch_vccz .LBB0_640
	s_waitcnt vmcnt(0)
	s_cmpk_gt_u32 s22, 0xff
	s_cbranch_scc1 .LBB0_651
	s_barrier

.LBB0_1185:
	ds_read_b128 v[88:91], v243
	ds_read_b128 v[96:99], v243 offset:1024
	ds_read_b128 v[108:111], v243 offset:2048
	ds_read_b128 v[116:119], v243 offset:3072
	s_add_u32 s26, s24, 0xfff80080
	s_addc_u32 s27, s25, -1
	s_cmp_eq_u32 s64, 28
	s_cselect_b32 s29, s17, s27
	s_cselect_b32 s28, s31, s26
	s_cselect_b32 s27, s15, s63
	s_cselect_b32 s26, s61, s62
	v_lshl_add_u64 v[176:177], s[24:25], 0, v[212:213]
	s_add_i32 m0, s23, 0xc000
	ds_read_b128 v[128:131], v244
	ds_read_b128 v[136:139], v244 offset:1024
	ds_read_b128 v[144:147], v244 offset:2048
	ds_read_b128 v[148:151], v244 offset:3072
	ds_read_b128 v[152:155], v244 offset:4096
	ds_read_b128 v[164:167], v244 offset:5120
	ds_read_b128 v[168:171], v244 offset:6144
	ds_read_b128 v[172:175], v244 offset:7168
	global_load_lds_dwordx4 v[176:177], off
	v_lshl_add_u64 v[176:177], s[24:25], 0, v[214:215]
	s_add_i32 m0, s23, 0xe000
	s_nop 0
	global_load_lds_dwordx4 v[176:177], off
	s_waitcnt lgkmcnt(0)
	s_barrier
	v_mfma_f32_16x16x32_f16 v[160:163], v[88:91], v[128:131], v[160:163]
	v_mfma_f32_16x16x32_f16 v[156:159], v[108:111], v[128:131], v[156:159]
	v_mfma_f32_16x16x32_f16 v[124:127], v[88:91], v[144:147], v[124:127]
	v_mfma_f32_16x16x32_f16 v[120:123], v[108:111], v[144:147], v[120:123]
	v_mfma_f32_16x16x32_f16 v[100:103], v[88:91], v[152:155], v[100:103]
	v_mfma_f32_16x16x32_f16 v[92:95], v[108:111], v[152:155], v[92:95]
	v_mfma_f32_16x16x32_f16 v[76:79], v[88:91], v[168:171], v[76:79]
	v_mfma_f32_16x16x32_f16 v[72:75], v[108:111], v[168:171], v[72:75]
	v_mfma_f32_16x16x32_f16 v[160:163], v[96:99], v[136:139], v[160:163]
	v_mfma_f32_16x16x32_f16 v[156:159], v[116:119], v[136:139], v[156:159]
	v_mfma_f32_16x16x32_f16 v[124:127], v[96:99], v[148:151], v[124:127]
	v_mfma_f32_16x16x32_f16 v[120:123], v[116:119], v[148:151], v[120:123]
	v_mfma_f32_16x16x32_f16 v[100:103], v[96:99], v[164:167], v[100:103]
	v_mfma_f32_16x16x32_f16 v[92:95], v[116:119], v[164:167], v[92:95]
	v_mfma_f32_16x16x32_f16 v[76:79], v[96:99], v[172:175], v[76:79]
	v_mfma_f32_16x16x32_f16 v[72:75], v[116:119], v[172:175], v[72:75]
	s_barrier
	s_add_i32 s65, s59, s44
	v_lshl_add_u64 v[192:193], s[26:27], 0, v[206:207]
	s_mov_b32 m0, s65
	ds_read_b128 v[176:179], v245
	ds_read_b128 v[180:183], v245 offset:1024
	ds_read_b128 v[184:187], v245 offset:2048
	ds_read_b128 v[188:191], v245 offset:3072
	global_load_lds_dwordx4 v[192:193], off
	v_lshl_add_u64 v[194:195], s[26:27], 0, v[210:211]
	s_add_i32 m0, s65, 0x2000
	s_nop 0
	global_load_lds_dwordx4 v[194:195], off
	s_waitcnt lgkmcnt(0)
	s_barrier
	v_mfma_f32_16x16x32_f16 v[140:143], v[176:179], v[128:131], v[140:143]
	v_mfma_f32_16x16x32_f16 v[112:115], v[176:179], v[144:147], v[112:115]
	v_mfma_f32_16x16x32_f16 v[104:107], v[184:187], v[144:147], v[104:107]
	v_mfma_f32_16x16x32_f16 v[84:87], v[176:179], v[152:155], v[84:87]
	v_mfma_f32_16x16x32_f16 v[80:83], v[184:187], v[152:155], v[80:83]
	v_mfma_f32_16x16x32_f16 v[68:71], v[176:179], v[168:171], v[68:71]
	v_mfma_f32_16x16x32_f16 v[64:67], v[184:187], v[168:171], v[64:67]
	v_mfma_f32_16x16x32_f16 v[140:143], v[180:183], v[136:139], v[140:143]
	v_mfma_f32_16x16x32_f16 v[128:131], v[184:187], v[128:131], v[132:135]
	v_mfma_f32_16x16x32_f16 v[112:115], v[180:183], v[148:151], v[112:115]
	v_mfma_f32_16x16x32_f16 v[104:107], v[188:191], v[148:151], v[104:107]
	v_mfma_f32_16x16x32_f16 v[84:87], v[180:183], v[164:167], v[84:87]
	v_mfma_f32_16x16x32_f16 v[80:83], v[188:191], v[164:167], v[80:83]
	v_mfma_f32_16x16x32_f16 v[68:71], v[180:183], v[172:175], v[68:71]
	v_mfma_f32_16x16x32_f16 v[64:67], v[188:191], v[172:175], v[64:67]
	v_mfma_f32_16x16x32_f16 v[128:131], v[188:191], v[136:139], v[128:131]
	s_mov_b32 m0, s23
	v_lshl_add_u64 v[196:197], s[28:29], 0, v[204:205]
	s_barrier
	ds_read_b128 v[132:135], v244 offset:16384
	ds_read_b128 v[136:139], v244 offset:17408
	ds_read_b128 v[144:147], v244 offset:18432
	ds_read_b128 v[148:151], v244 offset:19456
	ds_read_b128 v[152:155], v244 offset:20480
	ds_read_b128 v[164:167], v244 offset:21504
	ds_read_b128 v[168:171], v244 offset:22528
	ds_read_b128 v[172:175], v244 offset:23552
	global_load_lds_dwordx4 v[196:197], off
	v_lshl_add_u64 v[198:199], s[28:29], 0, v[208:209]
	s_mov_b32 m0, s45
	s_nop 0
	global_load_lds_dwordx4 v[198:199], off
	s_waitcnt lgkmcnt(0)
	s_barrier
	v_mfma_f32_16x16x32_f16 v[60:63], v[88:91], v[132:135], v[60:63]
	v_mfma_f32_16x16x32_f16 v[56:59], v[108:111], v[132:135], v[56:59]
	v_mfma_f32_16x16x32_f16 v[44:47], v[88:91], v[144:147], v[44:47]
	v_mfma_f32_16x16x32_f16 v[40:43], v[108:111], v[144:147], v[40:43]
	v_mfma_f32_16x16x32_f16 v[28:31], v[88:91], v[152:155], v[28:31]
	v_mfma_f32_16x16x32_f16 v[24:27], v[108:111], v[152:155], v[24:27]
	v_mfma_f32_16x16x32_f16 v[12:15], v[88:91], v[168:171], v[12:15]
	v_mfma_f32_16x16x32_f16 v[8:11], v[108:111], v[168:171], v[8:11]
	v_mfma_f32_16x16x32_f16 v[60:63], v[96:99], v[136:139], v[60:63]
	v_mfma_f32_16x16x32_f16 v[56:59], v[116:119], v[136:139], v[56:59]
	v_mfma_f32_16x16x32_f16 v[44:47], v[96:99], v[148:151], v[44:47]
	v_mfma_f32_16x16x32_f16 v[40:43], v[116:119], v[148:151], v[40:43]
	v_mfma_f32_16x16x32_f16 v[28:31], v[96:99], v[164:167], v[28:31]
	v_mfma_f32_16x16x32_f16 v[24:27], v[116:119], v[164:167], v[24:27]
	v_mfma_f32_16x16x32_f16 v[12:15], v[96:99], v[172:175], v[12:15]
	v_mfma_f32_16x16x32_f16 v[8:11], v[116:119], v[172:175], v[8:11]
	s_barrier
	s_add_u32 s66, s26, 0x80000
	s_addc_u32 s67, s27, 0
	s_add_i32 s65, s60, s44
	v_lshl_add_u64 v[88:89], s[66:67], 0, v[206:207]
	s_mov_b32 m0, s65
	s_nop 0
	global_load_lds_dwordx4 v[88:89], off
	v_lshl_add_u64 v[88:89], s[66:67], 0, v[210:211]
	s_add_i32 m0, s65, 0x2000
	s_nop 0
	global_load_lds_dwordx4 v[88:89], off
	s_waitcnt vmcnt(6)
	s_barrier
	v_mfma_f32_16x16x32_f16 v[52:55], v[176:179], v[132:135], v[52:55]
	v_mfma_f32_16x16x32_f16 v[48:51], v[184:187], v[132:135], v[48:51]
	v_mfma_f32_16x16x32_f16 v[36:39], v[176:179], v[144:147], v[36:39]
	v_mfma_f32_16x16x32_f16 v[32:35], v[184:187], v[144:147], v[32:35]
	v_mfma_f32_16x16x32_f16 v[20:23], v[176:179], v[152:155], v[20:23]
	v_mfma_f32_16x16x32_f16 v[16:19], v[184:187], v[152:155], v[16:19]
	v_mfma_f32_16x16x32_f16 v[4:7], v[176:179], v[168:171], v[4:7]
	v_mfma_f32_16x16x32_f16 v[0:3], v[184:187], v[168:171], v[0:3]
	v_mfma_f32_16x16x32_f16 v[52:55], v[180:183], v[136:139], v[52:55]
	v_mfma_f32_16x16x32_f16 v[48:51], v[188:191], v[136:139], v[48:51]
	v_mfma_f32_16x16x32_f16 v[36:39], v[180:183], v[148:151], v[36:39]
	v_mfma_f32_16x16x32_f16 v[32:35], v[188:191], v[148:151], v[32:35]
	v_mfma_f32_16x16x32_f16 v[20:23], v[180:183], v[164:167], v[20:23]
	v_mfma_f32_16x16x32_f16 v[16:19], v[188:191], v[164:167], v[16:19]
	v_mfma_f32_16x16x32_f16 v[4:7], v[180:183], v[172:175], v[4:7]
	v_mfma_f32_16x16x32_f16 v[0:3], v[188:191], v[172:175], v[0:3]
	s_add_i32 s65, 0, 0x18000
	v_add_u32_e32 v116, s65, v241
	s_barrier
	ds_read_b128 v[88:91], v116
	ds_read_b128 v[96:99], v116 offset:1024
	ds_read_b128 v[108:111], v116 offset:2048
	ds_read_b128 v[116:119], v116 offset:3072
	s_add_u32 s28, s28, 0x80000
	s_addc_u32 s29, s29, 0
	s_mov_b32 m0, s48
	v_lshl_add_u64 v[176:177], s[28:29], 0, v[204:205]
	ds_read_b128 v[132:135], v244 offset:32768
	ds_read_b128 v[136:139], v244 offset:33792
	ds_read_b128 v[144:147], v244 offset:34816
	ds_read_b128 v[148:151], v244 offset:35840
	ds_read_b128 v[152:155], v244 offset:36864
	ds_read_b128 v[164:167], v244 offset:37888
	ds_read_b128 v[168:171], v244 offset:38912
	ds_read_b128 v[172:175], v244 offset:39936
	global_load_lds_dwordx4 v[176:177], off
	v_lshl_add_u64 v[176:177], s[28:29], 0, v[208:209]
	s_mov_b32 m0, s49
	s_nop 0
	global_load_lds_dwordx4 v[176:177], off
	s_waitcnt lgkmcnt(0)
	s_barrier
	v_mfma_f32_16x16x32_f16 v[160:163], v[88:91], v[132:135], v[160:163]
	v_mfma_f32_16x16x32_f16 v[156:159], v[108:111], v[132:135], v[156:159]
	v_mfma_f32_16x16x32_f16 v[124:127], v[88:91], v[144:147], v[124:127]
	v_mfma_f32_16x16x32_f16 v[120:123], v[108:111], v[144:147], v[120:123]
	v_mfma_f32_16x16x32_f16 v[100:103], v[88:91], v[152:155], v[100:103]
	v_mfma_f32_16x16x32_f16 v[92:95], v[108:111], v[152:155], v[92:95]
	v_mfma_f32_16x16x32_f16 v[76:79], v[88:91], v[168:171], v[76:79]
	v_mfma_f32_16x16x32_f16 v[72:75], v[108:111], v[168:171], v[72:75]
	v_mfma_f32_16x16x32_f16 v[160:163], v[96:99], v[136:139], v[160:163]
	v_mfma_f32_16x16x32_f16 v[156:159], v[116:119], v[136:139], v[156:159]
	v_mfma_f32_16x16x32_f16 v[124:127], v[96:99], v[148:151], v[124:127]
	v_mfma_f32_16x16x32_f16 v[120:123], v[116:119], v[148:151], v[120:123]
	v_mfma_f32_16x16x32_f16 v[100:103], v[96:99], v[164:167], v[100:103]
	v_mfma_f32_16x16x32_f16 v[92:95], v[116:119], v[164:167], v[92:95]
	v_mfma_f32_16x16x32_f16 v[76:79], v[96:99], v[172:175], v[76:79]
	v_mfma_f32_16x16x32_f16 v[72:75], v[116:119], v[172:175], v[72:75]
	s_barrier
	s_add_i32 s28, 0, 0x1c000
	s_add_i32 s29, s65, s44
	v_add_u32_e32 v188, s28, v241
	v_lshl_add_u64 v[192:193], v[192:193], 0, s[6:7]
	s_mov_b32 m0, s29
	ds_read_b128 v[176:179], v188
	ds_read_b128 v[180:183], v188 offset:1024
	ds_read_b128 v[184:187], v188 offset:2048
	ds_read_b128 v[188:191], v188 offset:3072
	global_load_lds_dwordx4 v[192:193], off
	v_lshl_add_u64 v[192:193], v[194:195], 0, s[6:7]
	s_add_i32 m0, s29, 0x2000
	s_nop 0
	global_load_lds_dwordx4 v[192:193], off
	s_waitcnt lgkmcnt(0)
	s_barrier
	v_mfma_f32_16x16x32_f16 v[140:143], v[176:179], v[132:135], v[140:143]
	v_mfma_f32_16x16x32_f16 v[128:131], v[184:187], v[132:135], v[128:131]
	v_mfma_f32_16x16x32_f16 v[112:115], v[176:179], v[144:147], v[112:115]
	v_mfma_f32_16x16x32_f16 v[104:107], v[184:187], v[144:147], v[104:107]
	v_mfma_f32_16x16x32_f16 v[84:87], v[176:179], v[152:155], v[84:87]
	v_mfma_f32_16x16x32_f16 v[80:83], v[184:187], v[152:155], v[80:83]
	v_mfma_f32_16x16x32_f16 v[68:71], v[176:179], v[168:171], v[68:71]
	v_mfma_f32_16x16x32_f16 v[64:67], v[184:187], v[168:171], v[64:67]
	v_mfma_f32_16x16x32_f16 v[140:143], v[180:183], v[136:139], v[140:143]
	v_mfma_f32_16x16x32_f16 v[132:135], v[188:191], v[136:139], v[128:131]
	v_mfma_f32_16x16x32_f16 v[112:115], v[180:183], v[148:151], v[112:115]
	v_mfma_f32_16x16x32_f16 v[104:107], v[188:191], v[148:151], v[104:107]
	v_mfma_f32_16x16x32_f16 v[84:87], v[180:183], v[164:167], v[84:87]
	v_mfma_f32_16x16x32_f16 v[80:83], v[188:191], v[164:167], v[80:83]
	v_mfma_f32_16x16x32_f16 v[68:71], v[180:183], v[172:175], v[68:71]
	v_mfma_f32_16x16x32_f16 v[64:67], v[188:191], v[172:175], v[64:67]
	s_mov_b32 m0, s51
	v_lshl_add_u64 v[192:193], v[196:197], 0, s[6:7]
	s_barrier
	ds_read_b128 v[128:131], v244 offset:49152
	ds_read_b128 v[136:139], v244 offset:50176
	ds_read_b128 v[144:147], v244 offset:51200
	ds_read_b128 v[148:151], v244 offset:52224
	ds_read_b128 v[152:155], v244 offset:53248
	ds_read_b128 v[164:167], v244 offset:54272
	ds_read_b128 v[168:171], v244 offset:55296
	ds_read_b128 v[172:175], v244 offset:56320
	global_load_lds_dwordx4 v[192:193], off
	v_lshl_add_u64 v[192:193], v[198:199], 0, s[6:7]
	s_mov_b32 m0, s54
	s_nop 0
	global_load_lds_dwordx4 v[192:193], off
	s_waitcnt lgkmcnt(0)
	s_barrier
	v_mfma_f32_16x16x32_f16 v[60:63], v[88:91], v[128:131], v[60:63]
	v_mfma_f32_16x16x32_f16 v[56:59], v[108:111], v[128:131], v[56:59]
	v_mfma_f32_16x16x32_f16 v[44:47], v[88:91], v[144:147], v[44:47]
	v_mfma_f32_16x16x32_f16 v[40:43], v[108:111], v[144:147], v[40:43]
	v_mfma_f32_16x16x32_f16 v[28:31], v[88:91], v[152:155], v[28:31]
	v_mfma_f32_16x16x32_f16 v[24:27], v[108:111], v[152:155], v[24:27]
	v_mfma_f32_16x16x32_f16 v[12:15], v[88:91], v[168:171], v[12:15]
	v_mfma_f32_16x16x32_f16 v[8:11], v[108:111], v[168:171], v[8:11]
	v_mfma_f32_16x16x32_f16 v[60:63], v[96:99], v[136:139], v[60:63]
	v_mfma_f32_16x16x32_f16 v[56:59], v[116:119], v[136:139], v[56:59]
	v_mfma_f32_16x16x32_f16 v[44:47], v[96:99], v[148:151], v[44:47]
	v_mfma_f32_16x16x32_f16 v[40:43], v[116:119], v[148:151], v[40:43]
	v_mfma_f32_16x16x32_f16 v[28:31], v[96:99], v[164:167], v[28:31]
	v_mfma_f32_16x16x32_f16 v[24:27], v[116:119], v[164:167], v[24:27]
	v_mfma_f32_16x16x32_f16 v[12:15], v[96:99], v[172:175], v[12:15]
	v_mfma_f32_16x16x32_f16 v[8:11], v[116:119], v[172:175], v[8:11]
	s_barrier
	s_add_u32 s26, s26, 0x80080
	s_addc_u32 s27, s27, 0
	s_add_i32 s28, s28, s44
	v_lshl_add_u64 v[88:89], s[26:27], 0, v[206:207]
	s_mov_b32 m0, s28
	s_nop 0
	global_load_lds_dwordx4 v[88:89], off
	v_lshl_add_u64 v[88:89], s[26:27], 0, v[210:211]
	s_add_i32 m0, s28, 0x2000
	s_nop 0
	global_load_lds_dwordx4 v[88:89], off
	s_waitcnt vmcnt(6)
	s_barrier
	v_mfma_f32_16x16x32_f16 v[52:55], v[176:179], v[128:131], v[52:55]
	v_mfma_f32_16x16x32_f16 v[48:51], v[184:187], v[128:131], v[48:51]
	v_mfma_f32_16x16x32_f16 v[36:39], v[176:179], v[144:147], v[36:39]
	v_mfma_f32_16x16x32_f16 v[32:35], v[184:187], v[144:147], v[32:35]
	v_mfma_f32_16x16x32_f16 v[20:23], v[176:179], v[152:155], v[20:23]
	v_mfma_f32_16x16x32_f16 v[16:19], v[184:187], v[152:155], v[16:19]
	v_mfma_f32_16x16x32_f16 v[4:7], v[176:179], v[168:171], v[4:7]
	v_mfma_f32_16x16x32_f16 v[0:3], v[184:187], v[168:171], v[0:3]
	v_mfma_f32_16x16x32_f16 v[52:55], v[180:183], v[136:139], v[52:55]
	v_mfma_f32_16x16x32_f16 v[48:51], v[188:191], v[136:139], v[48:51]
	v_mfma_f32_16x16x32_f16 v[36:39], v[180:183], v[148:151], v[36:39]
	v_mfma_f32_16x16x32_f16 v[32:35], v[188:191], v[148:151], v[32:35]
	v_mfma_f32_16x16x32_f16 v[20:23], v[180:183], v[164:167], v[20:23]
	v_mfma_f32_16x16x32_f16 v[16:19], v[188:191], v[164:167], v[16:19]
	v_mfma_f32_16x16x32_f16 v[4:7], v[180:183], v[172:175], v[4:7]
	v_mfma_f32_16x16x32_f16 v[0:3], v[188:191], v[172:175], v[0:3]
	s_add_i32 s64, s64, 2
	s_add_u32 s24, s24, 0x100
	s_addc_u32 s25, s25, 0
	s_add_u32 s62, s62, 0x100
	s_addc_u32 s63, s63, 0
	s_cmp_gt_u32 s64, 29
	s_barrier
	s_cbranch_scc0 .LBB0_1185
	s_setprio 0
	s_lshl_b32 s15, s22, 8
	s_add_i32 s17, s15, 0xffffe000
	s_lshr_b32 s17, s17, 11
	s_mulk_i32 s17, 0x1800
	s_addk_i32 s17, 0x1800
	s_cmp_gt_i32 s22, 31
	s_cselect_b32 s24, s17, 0
	s_ashr_i32 s25, s24, 31
	v_lshl_or_b32 v128, s30, 8, v242
	s_lshl_b64 s[24:25], s[24:25], 2
	s_add_u32 s24, s42, s24
	v_ashrrev_i32_e32 v129, 31, v128
	v_add_u32_e32 v130, s15, v240
	s_addc_u32 s25, s43, s25
	v_lshlrev_b64 v[220:221], 1, v[128:129]
	v_ashrrev_i32_e32 v131, 31, v130
	v_lshl_add_u64 v[96:97], v[128:129], 2, s[24:25]
	v_lshl_add_u64 v[128:129], s[4:5], 0, v[220:221]
	v_lshlrev_b64 v[236:237], 12, v[130:131]
	v_lshl_add_u64 v[136:137], v[128:129], 0, v[236:237]
	global_load_dwordx4 v[108:111], v[96:97], off offset:16
	global_load_dwordx4 v[116:119], v[96:97], off
	global_load_dwordx4 v[88:91], v[96:97], off offset:528
	s_nop 0
	global_load_dwordx4 v[96:99], v[96:97], off offset:512
	s_nop 0
	global_load_dwordx4 v[246:249], v[136:137], off nt
	global_load_dwordx4 v[200:203], v[136:137], off offset:256 nt
	v_or_b32_e32 v136, 16, v130
	v_ashrrev_i32_e32 v137, 31, v136
	v_lshlrev_b64 v[234:235], 12, v[136:137]
	v_lshl_add_u64 v[136:137], v[128:129], 0, v[234:235]
	global_load_dwordx4 v[196:199], v[136:137], off nt
	global_load_dwordx4 v[192:195], v[136:137], off offset:256 nt
	v_or_b32_e32 v136, 32, v130
	v_ashrrev_i32_e32 v137, 31, v136
	v_lshlrev_b64 v[232:233], 12, v[136:137]
	v_lshl_add_u64 v[136:137], v[128:129], 0, v[232:233]
	global_load_dwordx4 v[188:191], v[136:137], off nt
	global_load_dwordx4 v[184:187], v[136:137], off offset:256 nt
	v_readlane_b32 s64, v254, 21
	v_readlane_b32 s68, v254, 25
	v_readlane_b32 s69, v254, 26
	s_mov_b64 s[56:57], s[68:69]
	v_or_b32_e32 v130, 48, v130
	v_ashrrev_i32_e32 v131, 31, v130
	v_lshlrev_b64 v[230:231], 12, v[130:131]
	v_lshl_add_u64 v[130:131], v[128:129], 0, v[230:231]
	global_load_dwordx4 v[180:183], v[130:131], off nt
	global_load_dwordx4 v[176:179], v[130:131], off offset:256 nt
	v_lshl_add_u64 v[228:229], v[236:237], 0, s[0:1]
	v_lshl_add_u64 v[130:131], v[128:129], 0, v[228:229]
	global_load_dwordx4 v[172:175], v[130:131], off nt
	global_load_dwordx4 v[168:171], v[130:131], off offset:256 nt
	v_lshl_add_u64 v[226:227], v[236:237], 0, s[8:9]
	v_lshl_add_u64 v[130:131], v[128:129], 0, v[226:227]
	global_load_dwordx4 v[164:167], v[130:131], off nt
	global_load_dwordx4 v[152:155], v[130:131], off offset:256 nt
	v_lshl_add_u64 v[224:225], v[236:237], 0, s[10:11]
	v_lshl_add_u64 v[130:131], v[128:129], 0, v[224:225]
	global_load_dwordx4 v[148:151], v[130:131], off nt
	global_load_dwordx4 v[144:147], v[130:131], off offset:256 nt
	v_lshl_add_u64 v[222:223], v[236:237], 0, s[12:13]
	v_lshl_add_u64 v[128:129], v[128:129], 0, v[222:223]
	global_load_dwordx4 v[136:139], v[128:129], off nt
	s_nop 0
	global_load_dwordx4 v[128:131], v[128:129], off offset:256 nt
	s_and_b64 vcc, exec, s[2:3]
	s_mov_b32 s30, s14
	s_mov_b32 s22, s16
	s_mov_b64 s[26:27], s[20:21]
	s_mov_b64 s[24:25], s[18:19]
	v_readlane_b32 s65, v254, 22
	v_readlane_b32 s66, v254, 23
	v_readlane_b32 s67, v254, 24
	v_readlane_b32 s70, v254, 27
	v_readlane_b32 s71, v254, 28
	v_readlane_b32 s72, v254, 29
	v_readlane_b32 s73, v254, 30
	v_readlane_b32 s74, v254, 31
	v_readlane_b32 s75, v254, 32
	v_readlane_b32 s76, v254, 33
	v_readlane_b32 s77, v254, 34
	v_readlane_b32 s78, v254, 35
	v_readlane_b32 s79, v254, 36
	s_waitcnt vmcnt(0)
	v_cvt_f32_f16_e32 v250, v246
	v_cvt_f32_f16_sdwa v251, v246 dst_sel:DWORD dst_unused:UNUSED_PAD src0_sel:WORD_1
	v_pk_fma_f32 v[160:161], v[160:161], v[116:117], v[250:251]
	s_nop 0
	v_cvt_pk_f16_f32 v246, v160, v161
	v_cvt_f32_f16_e32 v160, v248
	v_cvt_f32_f16_sdwa v161, v248 dst_sel:DWORD dst_unused:UNUSED_PAD src0_sel:WORD_1
	v_pk_fma_f32 v[156:157], v[156:157], v[108:109], v[160:161]
	s_nop 0
	v_cvt_pk_f16_f32 v248, v156, v157
	v_cvt_f32_f16_e32 v156, v247
	v_cvt_f32_f16_sdwa v157, v247 dst_sel:DWORD dst_unused:UNUSED_PAD src0_sel:WORD_1
	v_pk_fma_f32 v[156:157], v[162:163], v[118:119], v[156:157]
	s_nop 0
	v_cvt_pk_f16_f32 v247, v156, v157
	v_cvt_f32_f16_e32 v156, v249
	v_cvt_f32_f16_sdwa v157, v249 dst_sel:DWORD dst_unused:UNUSED_PAD src0_sel:WORD_1
	v_pk_fma_f32 v[156:157], v[158:159], v[110:111], v[156:157]
	s_nop 0
	v_cvt_pk_f16_f32 v249, v156, v157
	v_lshl_add_u64 v[156:157], s[56:57], 0, v[236:237]
	v_lshl_add_u64 v[160:161], v[156:157], 0, v[220:221]
	v_cvt_f32_f16_e32 v156, v200
	v_cvt_f32_f16_sdwa v157, v200 dst_sel:DWORD dst_unused:UNUSED_PAD src0_sel:WORD_1
	global_store_dwordx4 v[160:161], v[246:249], off
	v_pk_fma_f32 v[140:141], v[140:141], v[96:97], v[156:157]
	s_nop 0
	v_cvt_pk_f16_f32 v156, v140, v141
	v_cvt_f32_f16_e32 v140, v202
	v_cvt_f32_f16_sdwa v141, v202 dst_sel:DWORD dst_unused:UNUSED_PAD src0_sel:WORD_1
	v_pk_fma_f32 v[132:133], v[132:133], v[88:89], v[140:141]
	s_nop 0
	v_cvt_pk_f16_f32 v158, v132, v133
	v_cvt_f32_f16_e32 v132, v201
	v_cvt_f32_f16_sdwa v133, v201 dst_sel:DWORD dst_unused:UNUSED_PAD src0_sel:WORD_1
	v_pk_fma_f32 v[132:133], v[142:143], v[98:99], v[132:133]
	s_nop 0
	v_cvt_pk_f16_f32 v157, v132, v133
	v_cvt_f32_f16_e32 v132, v203
	v_cvt_f32_f16_sdwa v133, v203 dst_sel:DWORD dst_unused:UNUSED_PAD src0_sel:WORD_1
	v_pk_fma_f32 v[132:133], v[134:135], v[90:91], v[132:133]
	s_nop 0
	v_cvt_pk_f16_f32 v159, v132, v133
	v_cvt_f32_f16_e32 v132, v196
	v_cvt_f32_f16_sdwa v133, v196 dst_sel:DWORD dst_unused:UNUSED_PAD src0_sel:WORD_1
	global_store_dwordx4 v[160:161], v[156:159], off offset:256
	v_pk_fma_f32 v[124:125], v[124:125], v[116:117], v[132:133]
	s_nop 0
	v_cvt_pk_f16_f32 v132, v124, v125
	v_cvt_f32_f16_e32 v124, v198
	v_cvt_f32_f16_sdwa v125, v198 dst_sel:DWORD dst_unused:UNUSED_PAD src0_sel:WORD_1
	v_pk_fma_f32 v[120:121], v[120:121], v[108:109], v[124:125]
	s_nop 0
	v_cvt_pk_f16_f32 v134, v120, v121
	v_cvt_f32_f16_e32 v120, v197
	v_cvt_f32_f16_sdwa v121, v197 dst_sel:DWORD dst_unused:UNUSED_PAD src0_sel:WORD_1
	v_pk_fma_f32 v[120:121], v[126:127], v[118:119], v[120:121]
	s_nop 0
	v_cvt_pk_f16_f32 v133, v120, v121
	v_cvt_f32_f16_e32 v120, v199
	v_cvt_f32_f16_sdwa v121, v199 dst_sel:DWORD dst_unused:UNUSED_PAD src0_sel:WORD_1
	v_pk_fma_f32 v[120:121], v[122:123], v[110:111], v[120:121]
	s_nop 0
	v_cvt_pk_f16_f32 v135, v120, v121
	v_lshl_add_u64 v[120:121], s[56:57], 0, v[234:235]
	v_lshl_add_u64 v[124:125], v[120:121], 0, v[220:221]
	v_cvt_f32_f16_e32 v120, v192
	v_cvt_f32_f16_sdwa v121, v192 dst_sel:DWORD dst_unused:UNUSED_PAD src0_sel:WORD_1
	global_store_dwordx4 v[124:125], v[132:135], off
	v_pk_fma_f32 v[112:113], v[112:113], v[96:97], v[120:121]
	s_nop 0
	v_cvt_pk_f16_f32 v120, v112, v113
	v_cvt_f32_f16_e32 v112, v194
	v_cvt_f32_f16_sdwa v113, v194 dst_sel:DWORD dst_unused:UNUSED_PAD src0_sel:WORD_1
	v_pk_fma_f32 v[104:105], v[104:105], v[88:89], v[112:113]
	s_nop 0
	v_cvt_pk_f16_f32 v122, v104, v105
	v_cvt_f32_f16_e32 v104, v193
	v_cvt_f32_f16_sdwa v105, v193 dst_sel:DWORD dst_unused:UNUSED_PAD src0_sel:WORD_1
	v_pk_fma_f32 v[104:105], v[114:115], v[98:99], v[104:105]
	s_nop 0
	v_cvt_pk_f16_f32 v121, v104, v105
	v_cvt_f32_f16_e32 v104, v195
	v_cvt_f32_f16_sdwa v105, v195 dst_sel:DWORD dst_unused:UNUSED_PAD src0_sel:WORD_1
	v_pk_fma_f32 v[104:105], v[106:107], v[90:91], v[104:105]
	s_nop 0
	v_cvt_pk_f16_f32 v123, v104, v105
	v_cvt_f32_f16_e32 v104, v188
	v_cvt_f32_f16_sdwa v105, v188 dst_sel:DWORD dst_unused:UNUSED_PAD src0_sel:WORD_1
	global_store_dwordx4 v[124:125], v[120:123], off offset:256
	v_pk_fma_f32 v[100:101], v[100:101], v[116:117], v[104:105]
	s_nop 0
	v_cvt_pk_f16_f32 v104, v100, v101
	v_cvt_f32_f16_e32 v100, v190
	v_cvt_f32_f16_sdwa v101, v190 dst_sel:DWORD dst_unused:UNUSED_PAD src0_sel:WORD_1
	v_pk_fma_f32 v[92:93], v[92:93], v[108:109], v[100:101]
	s_nop 0
	v_cvt_pk_f16_f32 v106, v92, v93
	v_cvt_f32_f16_e32 v92, v189
	v_cvt_f32_f16_sdwa v93, v189 dst_sel:DWORD dst_unused:UNUSED_PAD src0_sel:WORD_1
	v_pk_fma_f32 v[92:93], v[102:103], v[118:119], v[92:93]
	s_nop 0
	v_cvt_pk_f16_f32 v105, v92, v93
	v_cvt_f32_f16_e32 v92, v191
	v_cvt_f32_f16_sdwa v93, v191 dst_sel:DWORD dst_unused:UNUSED_PAD src0_sel:WORD_1
	v_pk_fma_f32 v[92:93], v[94:95], v[110:111], v[92:93]
	s_nop 0
	v_cvt_pk_f16_f32 v107, v92, v93
	v_lshl_add_u64 v[92:93], s[56:57], 0, v[232:233]
	v_lshl_add_u64 v[100:101], v[92:93], 0, v[220:221]
	v_cvt_f32_f16_e32 v92, v184
	v_cvt_f32_f16_sdwa v93, v184 dst_sel:DWORD dst_unused:UNUSED_PAD src0_sel:WORD_1
	global_store_dwordx4 v[100:101], v[104:107], off
	v_pk_fma_f32 v[84:85], v[84:85], v[96:97], v[92:93]
	s_nop 0
	v_cvt_pk_f16_f32 v92, v84, v85
	v_cvt_f32_f16_e32 v84, v186
	v_cvt_f32_f16_sdwa v85, v186 dst_sel:DWORD dst_unused:UNUSED_PAD src0_sel:WORD_1
	v_pk_fma_f32 v[80:81], v[80:81], v[88:89], v[84:85]
	s_nop 0
	v_cvt_pk_f16_f32 v94, v80, v81
	v_cvt_f32_f16_e32 v80, v185
	v_cvt_f32_f16_sdwa v81, v185 dst_sel:DWORD dst_unused:UNUSED_PAD src0_sel:WORD_1
	v_pk_fma_f32 v[80:81], v[86:87], v[98:99], v[80:81]
	s_nop 0
	v_cvt_pk_f16_f32 v93, v80, v81
	v_cvt_f32_f16_e32 v80, v187
	v_cvt_f32_f16_sdwa v81, v187 dst_sel:DWORD dst_unused:UNUSED_PAD src0_sel:WORD_1
	v_pk_fma_f32 v[80:81], v[82:83], v[90:91], v[80:81]
	s_nop 0
	v_cvt_pk_f16_f32 v95, v80, v81
	v_cvt_f32_f16_e32 v80, v180
	v_cvt_f32_f16_sdwa v81, v180 dst_sel:DWORD dst_unused:UNUSED_PAD src0_sel:WORD_1
	global_store_dwordx4 v[100:101], v[92:95], off offset:256
	v_pk_fma_f32 v[76:77], v[76:77], v[116:117], v[80:81]
	s_nop 0
	v_cvt_pk_f16_f32 v80, v76, v77
	v_cvt_f32_f16_e32 v76, v182
	v_cvt_f32_f16_sdwa v77, v182 dst_sel:DWORD dst_unused:UNUSED_PAD src0_sel:WORD_1
	v_pk_fma_f32 v[72:73], v[72:73], v[108:109], v[76:77]
	s_nop 0
	v_cvt_pk_f16_f32 v82, v72, v73
	v_cvt_f32_f16_e32 v72, v181
	v_cvt_f32_f16_sdwa v73, v181 dst_sel:DWORD dst_unused:UNUSED_PAD src0_sel:WORD_1
	v_pk_fma_f32 v[72:73], v[78:79], v[118:119], v[72:73]
	s_nop 0
	v_cvt_pk_f16_f32 v81, v72, v73
	v_cvt_f32_f16_e32 v72, v183
	v_cvt_f32_f16_sdwa v73, v183 dst_sel:DWORD dst_unused:UNUSED_PAD src0_sel:WORD_1
	v_pk_fma_f32 v[72:73], v[74:75], v[110:111], v[72:73]
	s_nop 0
	v_cvt_pk_f16_f32 v83, v72, v73
	v_lshl_add_u64 v[72:73], s[56:57], 0, v[230:231]
	v_lshl_add_u64 v[76:77], v[72:73], 0, v[220:221]
	v_cvt_f32_f16_e32 v72, v176
	v_cvt_f32_f16_sdwa v73, v176 dst_sel:DWORD dst_unused:UNUSED_PAD src0_sel:WORD_1
	global_store_dwordx4 v[76:77], v[80:83], off
	v_pk_fma_f32 v[68:69], v[68:69], v[96:97], v[72:73]
	s_nop 0
	v_cvt_pk_f16_f32 v72, v68, v69
	v_cvt_f32_f16_e32 v68, v178
	v_cvt_f32_f16_sdwa v69, v178 dst_sel:DWORD dst_unused:UNUSED_PAD src0_sel:WORD_1
	v_pk_fma_f32 v[64:65], v[64:65], v[88:89], v[68:69]
	s_nop 0
	v_cvt_pk_f16_f32 v74, v64, v65
	v_cvt_f32_f16_e32 v64, v177
	v_cvt_f32_f16_sdwa v65, v177 dst_sel:DWORD dst_unused:UNUSED_PAD src0_sel:WORD_1
	v_pk_fma_f32 v[64:65], v[70:71], v[98:99], v[64:65]
	s_nop 0
	v_cvt_pk_f16_f32 v73, v64, v65
	v_cvt_f32_f16_e32 v64, v179
	v_cvt_f32_f16_sdwa v65, v179 dst_sel:DWORD dst_unused:UNUSED_PAD src0_sel:WORD_1
	v_pk_fma_f32 v[64:65], v[66:67], v[90:91], v[64:65]
	s_nop 0
	v_cvt_pk_f16_f32 v75, v64, v65
	v_cvt_f32_f16_e32 v64, v172
	v_cvt_f32_f16_sdwa v65, v172 dst_sel:DWORD dst_unused:UNUSED_PAD src0_sel:WORD_1
	global_store_dwordx4 v[76:77], v[72:75], off offset:256
	v_pk_fma_f32 v[60:61], v[60:61], v[116:117], v[64:65]
	s_nop 0
	v_cvt_pk_f16_f32 v64, v60, v61
	v_cvt_f32_f16_e32 v60, v174
	v_cvt_f32_f16_sdwa v61, v174 dst_sel:DWORD dst_unused:UNUSED_PAD src0_sel:WORD_1
	v_pk_fma_f32 v[56:57], v[56:57], v[108:109], v[60:61]
	s_nop 0
	v_cvt_pk_f16_f32 v66, v56, v57
	v_cvt_f32_f16_e32 v56, v173
	v_cvt_f32_f16_sdwa v57, v173 dst_sel:DWORD dst_unused:UNUSED_PAD src0_sel:WORD_1
	v_pk_fma_f32 v[56:57], v[62:63], v[118:119], v[56:57]
	s_nop 0
	v_cvt_pk_f16_f32 v65, v56, v57
	v_cvt_f32_f16_e32 v56, v175
	v_cvt_f32_f16_sdwa v57, v175 dst_sel:DWORD dst_unused:UNUSED_PAD src0_sel:WORD_1
	v_pk_fma_f32 v[56:57], v[58:59], v[110:111], v[56:57]
	s_nop 0
	v_cvt_pk_f16_f32 v67, v56, v57
	v_lshl_add_u64 v[56:57], s[56:57], 0, v[228:229]
	v_lshl_add_u64 v[60:61], v[56:57], 0, v[220:221]
	v_cvt_f32_f16_e32 v56, v168
	v_cvt_f32_f16_sdwa v57, v168 dst_sel:DWORD dst_unused:UNUSED_PAD src0_sel:WORD_1
	global_store_dwordx4 v[60:61], v[64:67], off
	v_pk_fma_f32 v[52:53], v[52:53], v[96:97], v[56:57]
	s_nop 0
	v_cvt_pk_f16_f32 v56, v52, v53
	v_cvt_f32_f16_e32 v52, v170
	v_cvt_f32_f16_sdwa v53, v170 dst_sel:DWORD dst_unused:UNUSED_PAD src0_sel:WORD_1
	v_pk_fma_f32 v[48:49], v[48:49], v[88:89], v[52:53]
	s_nop 0
	v_cvt_pk_f16_f32 v58, v48, v49
	v_cvt_f32_f16_e32 v48, v169
	v_cvt_f32_f16_sdwa v49, v169 dst_sel:DWORD dst_unused:UNUSED_PAD src0_sel:WORD_1
	v_pk_fma_f32 v[48:49], v[54:55], v[98:99], v[48:49]
	s_nop 0
	v_cvt_pk_f16_f32 v57, v48, v49
	v_cvt_f32_f16_e32 v48, v171
	v_cvt_f32_f16_sdwa v49, v171 dst_sel:DWORD dst_unused:UNUSED_PAD src0_sel:WORD_1
	v_pk_fma_f32 v[48:49], v[50:51], v[90:91], v[48:49]
	s_nop 0
	v_cvt_pk_f16_f32 v59, v48, v49
	v_cvt_f32_f16_e32 v48, v164
	v_cvt_f32_f16_sdwa v49, v164 dst_sel:DWORD dst_unused:UNUSED_PAD src0_sel:WORD_1
	global_store_dwordx4 v[60:61], v[56:59], off offset:256
	v_pk_fma_f32 v[44:45], v[44:45], v[116:117], v[48:49]
	s_nop 0
	v_cvt_pk_f16_f32 v48, v44, v45
	v_cvt_f32_f16_e32 v44, v166
	v_cvt_f32_f16_sdwa v45, v166 dst_sel:DWORD dst_unused:UNUSED_PAD src0_sel:WORD_1
	v_pk_fma_f32 v[40:41], v[40:41], v[108:109], v[44:45]
	s_nop 0
	v_cvt_pk_f16_f32 v50, v40, v41
	v_cvt_f32_f16_e32 v40, v165
	v_cvt_f32_f16_sdwa v41, v165 dst_sel:DWORD dst_unused:UNUSED_PAD src0_sel:WORD_1
	v_pk_fma_f32 v[40:41], v[46:47], v[118:119], v[40:41]
	s_nop 0
	v_cvt_pk_f16_f32 v49, v40, v41
	v_cvt_f32_f16_e32 v40, v167
	v_cvt_f32_f16_sdwa v41, v167 dst_sel:DWORD dst_unused:UNUSED_PAD src0_sel:WORD_1
	v_pk_fma_f32 v[40:41], v[42:43], v[110:111], v[40:41]
	s_nop 0
	v_cvt_pk_f16_f32 v51, v40, v41
	v_lshl_add_u64 v[40:41], s[56:57], 0, v[226:227]
	v_lshl_add_u64 v[44:45], v[40:41], 0, v[220:221]
	v_cvt_f32_f16_e32 v40, v152
	v_cvt_f32_f16_sdwa v41, v152 dst_sel:DWORD dst_unused:UNUSED_PAD src0_sel:WORD_1
	global_store_dwordx4 v[44:45], v[48:51], off
	v_pk_fma_f32 v[36:37], v[36:37], v[96:97], v[40:41]
	s_nop 0
	v_cvt_pk_f16_f32 v40, v36, v37
	v_cvt_f32_f16_e32 v36, v154
	v_cvt_f32_f16_sdwa v37, v154 dst_sel:DWORD dst_unused:UNUSED_PAD src0_sel:WORD_1
	v_pk_fma_f32 v[32:33], v[32:33], v[88:89], v[36:37]
	s_nop 0
	v_cvt_pk_f16_f32 v42, v32, v33
	v_cvt_f32_f16_e32 v32, v153
	v_cvt_f32_f16_sdwa v33, v153 dst_sel:DWORD dst_unused:UNUSED_PAD src0_sel:WORD_1
	v_pk_fma_f32 v[32:33], v[38:39], v[98:99], v[32:33]
	s_nop 0
	v_cvt_pk_f16_f32 v41, v32, v33
	v_cvt_f32_f16_e32 v32, v155
	v_cvt_f32_f16_sdwa v33, v155 dst_sel:DWORD dst_unused:UNUSED_PAD src0_sel:WORD_1
	v_pk_fma_f32 v[32:33], v[34:35], v[90:91], v[32:33]
	s_nop 0
	v_cvt_pk_f16_f32 v43, v32, v33
	v_cvt_f32_f16_e32 v32, v148
	v_cvt_f32_f16_sdwa v33, v148 dst_sel:DWORD dst_unused:UNUSED_PAD src0_sel:WORD_1
	global_store_dwordx4 v[44:45], v[40:43], off offset:256
	v_pk_fma_f32 v[28:29], v[28:29], v[116:117], v[32:33]
	s_nop 0
	v_cvt_pk_f16_f32 v32, v28, v29
	v_cvt_f32_f16_e32 v28, v150
	v_cvt_f32_f16_sdwa v29, v150 dst_sel:DWORD dst_unused:UNUSED_PAD src0_sel:WORD_1
	v_pk_fma_f32 v[24:25], v[24:25], v[108:109], v[28:29]
	s_nop 0
	v_cvt_pk_f16_f32 v34, v24, v25
	v_cvt_f32_f16_e32 v24, v149
	v_cvt_f32_f16_sdwa v25, v149 dst_sel:DWORD dst_unused:UNUSED_PAD src0_sel:WORD_1
	v_pk_fma_f32 v[24:25], v[30:31], v[118:119], v[24:25]
	s_nop 0
	v_cvt_pk_f16_f32 v33, v24, v25
	v_cvt_f32_f16_e32 v24, v151
	v_cvt_f32_f16_sdwa v25, v151 dst_sel:DWORD dst_unused:UNUSED_PAD src0_sel:WORD_1
	v_pk_fma_f32 v[24:25], v[26:27], v[110:111], v[24:25]
	s_nop 0
	v_cvt_pk_f16_f32 v35, v24, v25
	v_lshl_add_u64 v[24:25], s[56:57], 0, v[224:225]
	v_lshl_add_u64 v[28:29], v[24:25], 0, v[220:221]
	v_cvt_f32_f16_e32 v24, v144
	v_cvt_f32_f16_sdwa v25, v144 dst_sel:DWORD dst_unused:UNUSED_PAD src0_sel:WORD_1
	global_store_dwordx4 v[28:29], v[32:35], off
	v_pk_fma_f32 v[20:21], v[20:21], v[96:97], v[24:25]
	s_nop 0
	v_cvt_pk_f16_f32 v24, v20, v21
	v_cvt_f32_f16_e32 v20, v146
	v_cvt_f32_f16_sdwa v21, v146 dst_sel:DWORD dst_unused:UNUSED_PAD src0_sel:WORD_1
	v_pk_fma_f32 v[16:17], v[16:17], v[88:89], v[20:21]
	s_nop 0
	v_cvt_pk_f16_f32 v26, v16, v17
	v_cvt_f32_f16_e32 v16, v145
	v_cvt_f32_f16_sdwa v17, v145 dst_sel:DWORD dst_unused:UNUSED_PAD src0_sel:WORD_1
	v_pk_fma_f32 v[16:17], v[22:23], v[98:99], v[16:17]
	s_nop 0
	v_cvt_pk_f16_f32 v25, v16, v17
	v_cvt_f32_f16_e32 v16, v147
	v_cvt_f32_f16_sdwa v17, v147 dst_sel:DWORD dst_unused:UNUSED_PAD src0_sel:WORD_1
	v_pk_fma_f32 v[16:17], v[18:19], v[90:91], v[16:17]
	s_nop 0
	v_cvt_pk_f16_f32 v27, v16, v17
	v_cvt_f32_f16_e32 v16, v136
	v_cvt_f32_f16_sdwa v17, v136 dst_sel:DWORD dst_unused:UNUSED_PAD src0_sel:WORD_1
	global_store_dwordx4 v[28:29], v[24:27], off offset:256
	v_pk_fma_f32 v[12:13], v[12:13], v[116:117], v[16:17]
	s_nop 0
	v_cvt_pk_f16_f32 v16, v12, v13
	v_cvt_f32_f16_e32 v12, v138
	v_cvt_f32_f16_sdwa v13, v138 dst_sel:DWORD dst_unused:UNUSED_PAD src0_sel:WORD_1
	v_pk_fma_f32 v[8:9], v[8:9], v[108:109], v[12:13]
	s_nop 0
	v_cvt_pk_f16_f32 v18, v8, v9
	v_cvt_f32_f16_e32 v8, v137
	v_cvt_f32_f16_sdwa v9, v137 dst_sel:DWORD dst_unused:UNUSED_PAD src0_sel:WORD_1
	v_pk_fma_f32 v[8:9], v[14:15], v[118:119], v[8:9]
	s_nop 0
	v_cvt_pk_f16_f32 v17, v8, v9
	v_cvt_f32_f16_e32 v8, v139
	v_cvt_f32_f16_sdwa v9, v139 dst_sel:DWORD dst_unused:UNUSED_PAD src0_sel:WORD_1
	v_pk_fma_f32 v[8:9], v[10:11], v[110:111], v[8:9]
	s_nop 0
	v_cvt_pk_f16_f32 v19, v8, v9
	v_lshl_add_u64 v[8:9], s[56:57], 0, v[222:223]
	v_lshl_add_u64 v[12:13], v[8:9], 0, v[220:221]
	v_cvt_f32_f16_e32 v8, v128
	v_cvt_f32_f16_sdwa v9, v128 dst_sel:DWORD dst_unused:UNUSED_PAD src0_sel:WORD_1
	global_store_dwordx4 v[12:13], v[16:19], off
	v_pk_fma_f32 v[4:5], v[4:5], v[96:97], v[8:9]
	s_nop 0
	v_cvt_pk_f16_f32 v8, v4, v5
	v_cvt_f32_f16_e32 v4, v130
	v_cvt_f32_f16_sdwa v5, v130 dst_sel:DWORD dst_unused:UNUSED_PAD src0_sel:WORD_1
	v_pk_fma_f32 v[0:1], v[0:1], v[88:89], v[4:5]
	s_nop 0
	v_cvt_pk_f16_f32 v10, v0, v1
	v_cvt_f32_f16_e32 v0, v129
	v_cvt_f32_f16_sdwa v1, v129 dst_sel:DWORD dst_unused:UNUSED_PAD src0_sel:WORD_1
	v_pk_fma_f32 v[0:1], v[6:7], v[98:99], v[0:1]
	s_nop 0
	v_cvt_pk_f16_f32 v9, v0, v1
	v_cvt_f32_f16_e32 v0, v131
	v_cvt_f32_f16_sdwa v1, v131 dst_sel:DWORD dst_unused:UNUSED_PAD src0_sel:WORD_1
	v_pk_fma_f32 v[0:1], v[2:3], v[90:91], v[0:1]
	s_nop 0
	v_cvt_pk_f16_f32 v11, v0, v1
	global_store_dwordx4 v[12:13], v[8:11], off offset:256
	s_cbranch_vccz .LBB0_1178
	s_waitcnt vmcnt(0)
	s_cmpk_gt_u32 s34, 0xff
	s_cbranch_scc1 .LBB0_1189
	s_barrier
